# GLA scan interleaved into the FFT pair loop; grid-barrier acquire invalidate issued early by wave 1 (off the release critical path)
# speedup vs baseline: 1.0117x; 1.0053x over previous
.LBB0_104:
	v_readlane_b32 s0, v253, 3
	v_readlane_b32 s1, v253, 4
	s_mul_i32 s0, s1, s0
	v_readlane_b32 s1, v253, 1
	s_mul_i32 s0, s0, s1
	v_readlane_b32 s76, v253, 61
	v_writelane_b32 v254, s0, 30
	v_readlane_b32 s78, v253, 63
	v_readlane_b32 s79, v254, 0
	s_add_u32 s0, s78, 0xa0400
	s_addc_u32 s1, s79, 0
	s_add_u32 s68, s78, 0xa0600
	s_addc_u32 s69, s79, 0
	s_add_u32 s96, s78, 0xa0800
	s_addc_u32 s97, s79, 0
	s_add_u32 s50, s78, 0xa0a00
	v_writelane_b32 v254, s0, 32
	s_addc_u32 s51, s79, 0
	v_readlane_b32 s77, v253, 62
	v_writelane_b32 v254, s1, 33
	s_add_u32 s0, s78, 0xa0c00
	s_addc_u32 s1, s79, 0
	v_writelane_b32 v254, s0, 46
	s_waitcnt vmcnt(0)
	s_barrier
	s_nop 0
	v_writelane_b32 v254, s1, 47
	s_add_u32 s0, s78, 0xa0e00
	s_addc_u32 s1, s79, 0
	v_writelane_b32 v254, s0, 34
	s_nop 1
	v_writelane_b32 v254, s1, 35
	s_add_u32 s0, s78, 0xa1000
	s_addc_u32 s1, s79, 0
	v_writelane_b32 v254, s0, 17
	s_nop 1
	v_writelane_b32 v254, s1, 18
	s_add_u32 s0, s78, 0xa1200
	s_addc_u32 s1, s79, 0
	s_add_u32 s86, s78, 0xa0200
	v_writelane_b32 v254, s0, 1
	s_addc_u32 s87, s79, 0
	s_nop 0
	v_writelane_b32 v254, s1, 2
	s_add_u32 s0, s78, 0xa3500
	s_addc_u32 s1, s79, 0
	v_writelane_b32 v253, s0, 1
	s_nop 1
	v_writelane_b32 v253, s1, 2
	s_add_u32 s0, s78, 0xa0500
	s_addc_u32 s1, s79, 0
	v_writelane_b32 v254, s0, 3
	v_readlane_b32 s88, v253, 55
	v_readlane_b32 s89, v253, 56
	v_writelane_b32 v254, s1, 4
	s_add_u32 s0, s78, 0xa0700
	s_addc_u32 s1, s79, 0
	v_writelane_b32 v254, s0, 22
	s_nop 1
	v_writelane_b32 v254, s1, 23
	s_add_u32 s0, s78, 0xa0900
	s_addc_u32 s1, s79, 0
	v_writelane_b32 v254, s0, 24
	s_nop 1
	v_writelane_b32 v254, s1, 25
	s_add_u32 s0, s78, 0xa0b00
	s_addc_u32 s1, s79, 0
	s_add_u32 s92, s78, 0xa0d00
	v_writelane_b32 v254, s0, 26
	s_addc_u32 s93, s79, 0
	s_nop 0
	v_writelane_b32 v254, s1, 27
	s_add_u32 s0, s78, 0xa0f00
	s_addc_u32 s1, s79, 0
	v_writelane_b32 v254, s0, 28
	s_nop 1
	v_writelane_b32 v254, s1, 29
	s_add_u32 s0, s78, 0xa1100
	s_addc_u32 s1, s79, 0
	v_writelane_b32 v254, s0, 5
	s_nop 1
	v_writelane_b32 v254, s1, 6
	s_add_u32 s0, s78, 0xa1300
	s_addc_u32 s1, s79, 0
	v_writelane_b32 v254, s0, 9
	s_nop 1
	v_writelane_b32 v254, s1, 10
	s_add_u32 s0, s78, 0xa3400
	s_addc_u32 s1, s79, 0
	v_writelane_b32 v254, s0, 52
	s_nop 1
	v_writelane_b32 v254, s1, 53
	v_readfirstlane_b32 vcc_lo, v252
	s_lshr_b32 vcc_lo, vcc_lo, 6
	s_cmp_lg_u32 vcc_lo, 1
	s_cbranch_scc1 .Lbar_noinv_0
	buffer_inv sc1
.Lbar_noinv_0:
	s_and_saveexec_b64 s[0:1], s[88:89]
	v_readlane_b32 s40, v254, 11
	v_readlane_b32 s90, v253, 59
	v_readlane_b32 s41, v254, 12
	v_readlane_b32 s95, v253, 0
	v_readlane_b32 s91, v253, 60
	s_cbranch_execz .LBB0_156
	s_add_i32 s2, 0, 0x23fc0
	v_mov_b32_e32 v0, s2
	s_add_i32 s2, 0, 0x23fc4
	s_waitcnt vmcnt(0) expcnt(0) lgkmcnt(0)
	ds_read_b32 v2, v0
	v_mov_b32_e32 v0, s2
	s_add_i32 s2, 0, 0x23fc8
	v_mov_b32_e32 v1, s2
	ds_read_b32 v0, v0
	ds_read_b32 v1, v1
	s_waitcnt lgkmcnt(2)
	v_cmp_ne_u32_e32 vcc, 0, v2
	s_waitcnt lgkmcnt(0)
	v_readfirstlane_b32 s8, v1
	s_cbranch_vccnz .LBB0_120
	s_mov_b32 s9, 1
	v_mov_b32_e32 v16, 0
	s_branch .LBB0_108

.LBB0_135:
	s_or_b64 exec, exec, s[4:5]
	s_waitcnt vmcnt(0) lgkmcnt(0)
	s_waitcnt vmcnt(0)

.LBB0_153:
	s_or_b64 exec, exec, s[2:3]
	s_mov_b64 s[2:3], exec
	v_mbcnt_lo_u32_b32 v0, s2, 0
	v_mbcnt_hi_u32_b32 v0, s3, v0
	s_mov_b32 s7, 0
	v_cmp_eq_u32_e32 vcc, 0, v0
	s_waitcnt vmcnt(0)
	s_and_saveexec_b64 s[4:5], vcc
	s_cbranch_execz .LBB0_155
	s_add_i32 s6, s18, 0x900
	s_lshl_b64 s[6:7], s[6:7], 2
	v_readlane_b32 s8, v253, 5
	v_readlane_b32 s9, v253, 6
	s_add_u32 s6, s8, s6
	s_addc_u32 s7, s9, s7
	s_bcnt1_i32_b64 s2, s[2:3]
	v_mov_b32_e32 v0, 0
	v_mov_b32_e32 v1, s2
	global_atomic_add v0, v1, s[6:7]

.LBB0_156:
	s_or_b64 exec, exec, s[0:1]
	s_add_u32 s16, s78, 0xaa00000
	s_addc_u32 s17, s79, 0
	s_add_u32 s18, s78, 0x8a00000
	s_addc_u32 s19, s79, 0
	s_cmpk_lt_i32 s95, 0x580
	s_cselect_b64 s[2:3], -1, 0
	v_writelane_b32 v254, s2, 54
	v_readlane_b32 s0, v253, 3
	v_readlane_b32 s1, v253, 4
	v_writelane_b32 v254, s3, 55
	v_mov_b32_e32 v14, v252
	v_writelane_b32 v254, s86, 56
	s_waitcnt vmcnt(0) lgkmcnt(0)
	s_barrier
	s_ashr_i32 s34, s0, 31
	s_ashr_i32 s80, s95, 31
	s_and_b64 vcc, exec, s[2:3]
	v_readfirstlane_b32 s1, v14
	v_writelane_b32 v254, s87, 57
	s_cbranch_vccz .LBB0_172
	v_lshlrev_b32_e32 v0, 4, v14
	v_add_u32_e32 v1, 0x2000, v0
	v_ashrrev_i32_e32 v2, 31, v1
	v_lshrrev_b32_e32 v2, 22, v2
	v_add_u32_e32 v2, v1, v2
	v_ashrrev_i32_e32 v8, 10, v2
	v_mul_i32_i24_e32 v2, 0x400, v8
	v_sub_u32_e32 v1, v1, v2
	v_lshrrev_b32_e32 v2, 4, v1
	v_bitop3_b32 v1, v2, v1, 32 bitop3:0x6c
	v_ashrrev_i32_e32 v2, 31, v1
	v_lshrrev_b32_e32 v2, 26, v2
	v_add_u32_e32 v2, v1, v2
	v_lshlrev_b32_e32 v3, 3, v8
	v_ashrrev_i32_e32 v9, 6, v2
	v_and_b32_e32 v3, -16, v3
	v_add_u32_e32 v3, v9, v3
	v_and_b32_e32 v4, 3, v9
	s_mov_b32 s0, 0xfffe0
	v_lshrrev_b32_e32 v5, 2, v3
	v_lshlrev_b32_e32 v6, 1, v3
	v_and_b32_e32 v2, 0xc0, v2
	v_and_or_b32 v4, v3, s0, v4
	v_and_b32_e32 v5, 4, v5
	v_and_b32_e32 v6, 24, v6
	v_sub_u32_e32 v1, v1, v2
	v_mov_b32_e32 v2, 1
	v_or3_b32 v4, v4, v5, v6
	v_lshlrev_b32_e32 v5, 5, v8
	v_ashrrev_i16_sdwa v1, v2, sext(v1) dst_sel:DWORD dst_unused:UNUSED_PAD src0_sel:DWORD src1_sel:BYTE_0
	v_and_b32_e32 v5, 32, v5
	v_bfe_i32 v10, v1, 0, 16
	v_add_lshl_u32 v1, v5, v10, 1
	v_lshl_add_u32 v128, v4, 12, v1
	v_lshl_add_u32 v130, v3, 12, v1
	v_bfe_i32 v1, v14, 27, 1
	v_lshrrev_b32_e32 v1, 22, v1
	v_add_u32_e32 v1, v0, v1
	v_and_b32_e32 v1, 0xfffffc00, v1
	v_sub_u32_e32 v0, v0, v1
	v_lshrrev_b32_e32 v1, 4, v0
	v_ashrrev_i32_e32 v3, 31, v14
	v_bitop3_b32 v0, v1, v0, 32 bitop3:0x6c
	v_lshrrev_b32_e32 v3, 26, v3
	v_ashrrev_i32_e32 v1, 31, v0
	v_add_u32_e32 v3, v14, v3
	v_lshrrev_b32_e32 v1, 26, v1
	v_ashrrev_i32_e32 v12, 6, v3
	v_add_u32_e32 v1, v0, v1
	v_lshlrev_b32_e32 v3, 3, v12
	v_ashrrev_i32_e32 v11, 6, v1
	v_and_b32_e32 v3, -16, v3
	v_add_u32_e32 v3, v11, v3
	v_and_b32_e32 v4, 3, v11
	v_and_or_b32 v4, v3, s0, v4
	s_lshr_b32 s0, s80, 29
	s_add_i32 s0, s95, s0
	s_ashr_i32 s6, s1, 6
	s_ashr_i32 s2, s0, 3
	s_and_b32 s0, s0, -8
	s_ashr_i32 s7, s1, 8
	s_lshl_b32 s25, s6, 10
	s_sub_i32 s0, s95, s0
	s_cmp_lt_i32 s0, 0
	s_movk_i32 s33, 0xb1
	s_cselect_b32 s3, s33, 0xb0
	s_mul_i32 s0, s0, s3
	s_add_i32 s0, s0, s2
	s_mul_hi_i32 s2, s0, 0x2e8ba2e9
	s_lshr_b32 s3, s2, 31
	s_ashr_i32 s2, s2, 6
	s_add_i32 s2, s2, s3
	s_lshl_b32 s3, s2, 3
	s_mulk_i32 s2, 0x160
	s_sub_i32 s2, s0, s2
	s_sext_i32_i16 s0, s2
	s_bfe_u32 s0, s0, 0x3001c
	s_add_i32 s4, s2, s0
	s_sext_i32_i16 s0, s4
	s_and_b32 s4, s4, 0xfff8
	s_sub_i32 s2, s2, s4
	s_sext_i32_i16 s2, s2
	v_lshrrev_b32_e32 v5, 2, v3
	v_lshlrev_b32_e32 v6, 1, v3
	v_and_b32_e32 v1, 0xc0, v1
	s_lshr_b32 s0, s0, 3
	s_add_i32 s2, s3, s2
	v_and_b32_e32 v5, 4, v5
	v_and_b32_e32 v6, 24, v6
	v_sub_u32_e32 v0, v0, v1
	s_ashr_i32 s3, s2, 31
	s_bfe_i64 s[8:9], s[0:1], 0x100000
	v_or3_b32 v4, v4, v5, v6
	v_lshlrev_b32_e32 v5, 5, v12
	v_ashrrev_i16_sdwa v0, v2, sext(v0) dst_sel:DWORD dst_unused:UNUSED_PAD src0_sel:DWORD src1_sel:BYTE_0
	s_lshl_b64 s[4:5], s[2:3], 20
	s_lshl_b64 s[8:9], s[8:9], 20
	v_and_b32_e32 v5, 32, v5
	v_bfe_i32 v13, v0, 0, 16
	s_add_u32 s28, s40, s8
	v_add_lshl_u32 v0, v5, v13, 1
	s_addc_u32 s29, s41, s9
	s_add_i32 s35, s25, 0
	v_lshl_add_u32 v132, v4, 12, v0
	v_and_b32_e32 v238, 15, v14
	v_lshl_or_b32 v238, s7, 6, v238
	v_lshl_add_u32 v238, s2, 8, v238
	v_lshlrev_b32_e32 v238, 2, v238
	global_load_dword v230, v238, s[78:79]
	global_load_dword v231, v238, s[78:79] offset:64
	global_load_dword v232, v238, s[78:79] offset:128
	global_load_dword v233, v238, s[78:79] offset:192
	global_load_dword v234, v238, s[78:79] offset:512
	global_load_dword v235, v238, s[78:79] offset:576
	global_load_dword v236, v238, s[78:79] offset:640
	global_load_dword v237, v238, s[78:79] offset:704
	s_add_i32 m0, s35, 0x10000
	v_lshl_add_u32 v134, v3, 12, v0
	global_load_lds_dwordx4 v132, s[28:29]
	s_add_i32 m0, s35, 0x12000
	s_add_u32 s8, s28, 0x80000
	global_load_lds_dwordx4 v128, s[28:29]
	s_addc_u32 s9, s29, 0
	s_add_i32 m0, s35, 0x14000
	v_mov_b32_e32 v133, 0
	global_load_lds_dwordx4 v132, s[8:9]
	s_add_i32 m0, s35, 0x16000
	s_add_u32 s26, s18, s4
	s_addc_u32 s27, s19, s5
	s_add_i32 s36, s35, 0x2000
	global_load_lds_dwordx4 v128, s[8:9]
	s_mov_b32 m0, s35
	s_add_u32 s4, s26, 0x80000
	global_load_lds_dwordx4 v134, s[26:27]
	s_mov_b32 m0, s36
	s_addc_u32 s5, s27, 0
	s_add_i32 s37, s35, 0x4000
	global_load_lds_dwordx4 v130, s[26:27]
	s_mov_b32 m0, s37
	s_add_i32 s38, s35, 0x6000
	global_load_lds_dwordx4 v134, s[4:5]
	s_mov_b32 m0, s38
	v_mov_b32_e32 v129, v133
	global_load_lds_dwordx4 v130, s[4:5]
	v_mov_b32_e32 v135, v133
	v_mov_b32_e32 v131, v133
	s_cmp_eq_u32 s7, 1
	s_mov_b32 s39, 0
	v_lshl_add_u64 v[6:7], s[28:29], 0, v[132:133]
	v_lshl_add_u64 v[4:5], s[28:29], 0, v[128:129]
	v_lshl_add_u64 v[0:1], s[26:27], 0, v[134:135]
	s_cselect_b64 s[4:5], -1, 0
	s_cmp_lg_u32 s7, 1
	v_lshl_add_u64 v[2:3], s[26:27], 0, v[130:131]
	s_cbranch_scc1 .LBB0_159
	s_barrier

.LBB0_188:
	s_waitcnt vmcnt(0)
	s_barrier
	v_readfirstlane_b32 vcc_lo, v252
	s_lshr_b32 vcc_lo, vcc_lo, 6
	s_cmp_lg_u32 vcc_lo, 1
	s_cbranch_scc1 .Lbar_noinv_1
	buffer_inv sc1
.Lbar_noinv_1:
	s_and_saveexec_b64 s[2:3], s[88:89]
	s_cbranch_execz .LBB0_240
	s_add_i32 s4, 0, 0x23fc0
	v_mov_b32_e32 v0, s4
	s_add_i32 s4, 0, 0x23fc4
	s_waitcnt vmcnt(0) expcnt(0) lgkmcnt(0)
	ds_read_b32 v2, v0
	v_mov_b32_e32 v0, s4
	s_add_i32 s4, 0, 0x23fc8
	v_mov_b32_e32 v1, s4
	ds_read_b32 v0, v0
	ds_read_b32 v1, v1
	s_waitcnt lgkmcnt(2)
	v_cmp_ne_u32_e32 vcc, 0, v2
	s_waitcnt lgkmcnt(0)
	v_readfirstlane_b32 s10, v1
	s_cbranch_vccnz .LBB0_204
	s_mov_b32 s11, 1
	v_mov_b32_e32 v16, 0
	s_branch .LBB0_192

.LBB0_219:
	s_or_b64 exec, exec, s[6:7]
	s_waitcnt vmcnt(0) lgkmcnt(0)
	s_waitcnt vmcnt(0)

.LBB0_237:
	s_or_b64 exec, exec, s[4:5]
	s_mov_b64 s[4:5], exec
	v_mbcnt_lo_u32_b32 v0, s4, 0
	v_mbcnt_hi_u32_b32 v0, s5, v0
	s_mov_b32 s9, 0
	v_cmp_eq_u32_e32 vcc, 0, v0
	s_waitcnt vmcnt(0)
	s_and_saveexec_b64 s[6:7], vcc
	s_cbranch_execz .LBB0_239
	s_add_i32 s8, s20, 0x900
	s_lshl_b64 s[8:9], s[8:9], 2
	v_readlane_b32 s10, v253, 5
	v_readlane_b32 s11, v253, 6
	s_add_u32 s8, s10, s8
	s_addc_u32 s9, s11, s9
	s_bcnt1_i32_b64 s4, s[4:5]
	v_mov_b32_e32 v0, 0
	v_mov_b32_e32 v1, s4
	global_atomic_add v0, v1, s[8:9]

.LBB0_240:
	s_or_b64 exec, exec, s[2:3]
	s_cmpk_lt_i32 s95, 0x100
	v_mov_b32_e32 v8, v252
	s_cselect_b64 s[74:75], -1, 0
	s_waitcnt vmcnt(0) lgkmcnt(0)
	s_barrier
	s_and_b64 vcc, exec, s[74:75]
	v_readfirstlane_b32 s4, v8
	s_cbranch_vccz .LBB0_246
	s_lshr_b32 s2, s80, 29
	s_add_i32 s5, s95, s2
	s_and_b32 s2, s5, -8
	s_sub_i32 s6, s95, s2
	s_cmp_gt_i32 s6, -1
	s_cbranch_scc0 .LBB0_243
	s_lshl_b32 s7, s6, 5
	s_cbranch_execz .LBB0_244
	s_branch .LBB0_245

.LBB0_286:
	s_waitcnt vmcnt(0)
	s_waitcnt lgkmcnt(0)
	s_barrier
	v_readfirstlane_b32 vcc_lo, v252
	s_lshr_b32 vcc_lo, vcc_lo, 6
	s_cmp_lg_u32 vcc_lo, 1
	s_cbranch_scc1 .Lbar_noinv_2
	buffer_inv sc1

.LBB0_338:
	s_or_b64 exec, exec, s[2:3]
	v_mov_b32_e32 v14, v252
	s_waitcnt vmcnt(0) lgkmcnt(0)
	s_barrier
	s_cmpk_lt_i32 s95, 0x300
	v_writelane_b32 v254, s80, 44
	v_readfirstlane_b32 s5, v14
	s_cbranch_scc0 .LBB0_354
	v_lshlrev_b32_e32 v0, 4, v14
	v_add_u32_e32 v1, 0x2000, v0
	v_ashrrev_i32_e32 v2, 31, v1
	v_lshrrev_b32_e32 v2, 22, v2
	v_add_u32_e32 v2, v1, v2
	v_ashrrev_i32_e32 v8, 10, v2
	v_mul_i32_i24_e32 v2, 0x400, v8
	v_sub_u32_e32 v1, v1, v2
	v_lshrrev_b32_e32 v2, 4, v1
	v_bitop3_b32 v1, v2, v1, 32 bitop3:0x6c
	v_ashrrev_i32_e32 v2, 31, v1
	v_lshrrev_b32_e32 v2, 26, v2
	v_add_u32_e32 v2, v1, v2
	v_lshlrev_b32_e32 v3, 3, v8
	v_ashrrev_i32_e32 v9, 6, v2
	v_and_b32_e32 v3, -16, v3
	v_add_u32_e32 v3, v9, v3
	v_and_b32_e32 v4, 3, v9
	s_mov_b32 s2, 0xfffe0
	v_lshrrev_b32_e32 v5, 2, v3
	v_lshlrev_b32_e32 v6, 1, v3
	v_and_b32_e32 v2, 0xc0, v2
	v_and_or_b32 v4, v3, s2, v4
	v_and_b32_e32 v5, 4, v5
	v_and_b32_e32 v6, 24, v6
	v_sub_u32_e32 v1, v1, v2
	v_mov_b32_e32 v2, 1
	v_or3_b32 v4, v4, v5, v6
	v_lshlrev_b32_e32 v5, 5, v8
	v_ashrrev_i16_sdwa v1, v2, sext(v1) dst_sel:DWORD dst_unused:UNUSED_PAD src0_sel:DWORD src1_sel:BYTE_0
	v_and_b32_e32 v5, 32, v5
	v_bfe_i32 v10, v1, 0, 16
	v_add_lshl_u32 v1, v5, v10, 1
	v_lshl_add_u32 v128, v4, 12, v1
	v_lshl_add_u32 v130, v3, 12, v1
	v_bfe_i32 v1, v14, 27, 1
	v_lshrrev_b32_e32 v1, 22, v1
	v_add_u32_e32 v1, v0, v1
	v_and_b32_e32 v1, 0xfffffc00, v1
	v_sub_u32_e32 v0, v0, v1
	v_lshrrev_b32_e32 v1, 4, v0
	v_ashrrev_i32_e32 v3, 31, v14
	v_bitop3_b32 v0, v1, v0, 32 bitop3:0x6c
	v_lshrrev_b32_e32 v3, 26, v3
	v_ashrrev_i32_e32 v1, 31, v0
	v_add_u32_e32 v3, v14, v3
	v_lshrrev_b32_e32 v1, 26, v1
	v_ashrrev_i32_e32 v12, 6, v3
	v_add_u32_e32 v1, v0, v1
	v_lshlrev_b32_e32 v3, 3, v12
	v_ashrrev_i32_e32 v11, 6, v1
	v_and_b32_e32 v3, -16, v3
	v_add_u32_e32 v3, v11, v3
	v_and_b32_e32 v4, 3, v11
	v_and_or_b32 v4, v3, s2, v4
	s_lshr_b32 s2, s80, 29
	s_add_i32 s2, s95, s2
	s_ashr_i32 s6, s5, 6
	s_ashr_i32 s3, s2, 3
	s_and_b32 s2, s2, -8
	s_ashr_i32 s7, s5, 8
	s_lshl_b32 s20, s6, 10
	s_sub_i32 s2, s95, s2
	s_cmp_lt_i32 s2, 0
	s_movk_i32 s21, 0x61
	s_cselect_b32 s4, s21, 0x60
	s_mul_i32 s2, s2, s4
	s_add_i32 s2, s2, s3
	s_mul_hi_i32 s3, s2, 0x2aaaaaab
	s_lshr_b32 s4, s3, 31
	s_ashr_i32 s3, s3, 5
	s_add_i32 s3, s3, s4
	s_lshl_b32 s8, s3, 3
	s_mulk_i32 s3, 0xc0
	s_sub_i32 s2, s2, s3
	s_sext_i32_i16 s3, s2
	s_bfe_u32 s3, s3, 0x3001c
	s_add_i32 s3, s2, s3
	s_sext_i32_i16 s4, s3
	s_and_b32 s3, s3, 0xfff8
	s_sub_i32 s2, s2, s3
	s_sext_i32_i16 s2, s2
	v_lshrrev_b32_e32 v5, 2, v3
	v_lshlrev_b32_e32 v6, 1, v3
	v_and_b32_e32 v1, 0xc0, v1
	s_lshr_b32 s4, s4, 3
	s_add_i32 s28, s8, s2
	v_and_b32_e32 v5, 4, v5
	v_and_b32_e32 v6, 24, v6
	v_sub_u32_e32 v0, v0, v1
	s_ashr_i32 s29, s28, 31
	s_bfe_i64 s[8:9], s[4:5], 0x100000
	v_or3_b32 v4, v4, v5, v6
	v_lshlrev_b32_e32 v5, 5, v12
	v_ashrrev_i16_sdwa v0, v2, sext(v0) dst_sel:DWORD dst_unused:UNUSED_PAD src0_sel:DWORD src1_sel:BYTE_0
	s_lshl_b64 s[2:3], s[28:29], 20
	s_lshl_b64 s[8:9], s[8:9], 20
	v_and_b32_e32 v5, 32, v5
	v_bfe_i32 v13, v0, 0, 16
	s_add_u32 s82, s0, s8
	v_add_lshl_u32 v0, v5, v13, 1
	s_addc_u32 s83, s1, s9
	s_add_i32 s22, s20, 0
	v_lshl_add_u32 v132, v4, 12, v0
	v_and_b32_e32 v238, 15, v14
	v_lshl_or_b32 v238, s7, 6, v238
	v_lshl_add_u32 v238, s28, 8, v238
	v_lshlrev_b32_e32 v238, 2, v238
	global_load_dword v230, v238, s[90:91]
	global_load_dword v231, v238, s[90:91] offset:64
	global_load_dword v232, v238, s[90:91] offset:128
	global_load_dword v233, v238, s[90:91] offset:192
	global_load_dword v234, v238, s[90:91] offset:512
	global_load_dword v235, v238, s[90:91] offset:576
	global_load_dword v236, v238, s[90:91] offset:640
	global_load_dword v237, v238, s[90:91] offset:704
	s_add_i32 m0, s22, 0x10000
	v_lshl_add_u32 v134, v3, 12, v0
	global_load_lds_dwordx4 v132, s[82:83]
	s_add_i32 m0, s22, 0x12000
	s_add_u32 s8, s82, 0x80000
	global_load_lds_dwordx4 v128, s[82:83]
	s_addc_u32 s9, s83, 0
	s_add_i32 m0, s22, 0x14000
	v_mov_b32_e32 v133, 0
	global_load_lds_dwordx4 v132, s[8:9]
	s_add_i32 m0, s22, 0x16000
	s_add_u32 s80, s18, s2
	s_addc_u32 s81, s19, s3
	s_add_i32 s23, s22, 0x2000
	global_load_lds_dwordx4 v128, s[8:9]
	s_mov_b32 m0, s22
	s_add_u32 s2, s80, 0x80000
	global_load_lds_dwordx4 v134, s[80:81]
	s_mov_b32 m0, s23
	s_addc_u32 s3, s81, 0
	s_add_i32 s24, s22, 0x4000
	global_load_lds_dwordx4 v130, s[80:81]
	s_mov_b32 m0, s24
	s_add_i32 s25, s22, 0x6000
	global_load_lds_dwordx4 v134, s[2:3]
	s_mov_b32 m0, s25
	v_mov_b32_e32 v129, v133
	global_load_lds_dwordx4 v130, s[2:3]
	v_mov_b32_e32 v135, v133
	v_mov_b32_e32 v131, v133
	s_cmp_eq_u32 s7, 1
	s_mov_b32 s33, 0
	v_lshl_add_u64 v[6:7], s[82:83], 0, v[132:133]
	v_lshl_add_u64 v[4:5], s[82:83], 0, v[128:129]
	v_lshl_add_u64 v[0:1], s[80:81], 0, v[134:135]
	s_cselect_b64 s[2:3], -1, 0
	s_cmp_lg_u32 s7, 1
	v_lshl_add_u64 v[2:3], s[80:81], 0, v[130:131]
	s_cbranch_scc1 .LBB0_341
	s_barrier

.Lbar_noinv_3:
	s_and_saveexec_b64 s[0:1], s[88:89]
	v_readlane_b32 s22, v253, 1
	v_readlane_b32 s23, v253, 2
	s_cbranch_execz .LBB0_415
	s_add_i32 s2, 0, 0x23fc0
	v_mov_b32_e32 v0, s2
	s_add_i32 s2, 0, 0x23fc4
	s_waitcnt vmcnt(0) expcnt(0) lgkmcnt(0)
	ds_read_b32 v2, v0
	v_mov_b32_e32 v0, s2
	s_add_i32 s2, 0, 0x23fc8
	v_mov_b32_e32 v1, s2
	ds_read_b32 v0, v0
	ds_read_b32 v1, v1
	s_waitcnt lgkmcnt(2)
	v_cmp_ne_u32_e32 vcc, 0, v2
	s_waitcnt lgkmcnt(0)
	v_readfirstlane_b32 s8, v1
	s_cbranch_vccnz .LBB0_379
	s_mov_b32 s9, 1
	v_mov_b32_e32 v16, 0
	s_branch .LBB0_367

.LBB0_412:
	s_or_b64 exec, exec, s[2:3]
	s_mov_b64 s[2:3], exec
	v_mbcnt_lo_u32_b32 v0, s2, 0
	v_mbcnt_hi_u32_b32 v0, s3, v0
	s_mov_b32 s7, 0
	v_cmp_eq_u32_e32 vcc, 0, v0
	s_waitcnt vmcnt(0)
	s_and_saveexec_b64 s[4:5], vcc
	s_cbranch_execz .LBB0_414
	s_add_i32 s6, s20, 0x900
	s_lshl_b64 s[6:7], s[6:7], 2
	v_readlane_b32 s8, v253, 5
	v_readlane_b32 s9, v253, 6
	s_add_u32 s6, s8, s6
	s_addc_u32 s7, s9, s7
	s_bcnt1_i32_b64 s2, s[2:3]
	v_mov_b32_e32 v0, 0
	v_mov_b32_e32 v1, s2
	global_atomic_add v0, v1, s[6:7]

.LBB0_415:
	v_writelane_b32 v255, s31, 2
	v_writelane_b32 v255, s30, 3
	s_or_b64 exec, exec, s[0:1]
	v_mov_b32_e32 v8, v252
	v_writelane_b32 v255, s74, 4
	s_waitcnt vmcnt(0) lgkmcnt(0)
	s_barrier
	v_writelane_b32 v255, s75, 5
	v_readfirstlane_b32 s4, v8
	s_and_b64 vcc, exec, s[74:75]
	s_cbranch_vccz .LBB0_417
	s_lshr_b32 s0, s80, 29
	s_add_i32 s0, s95, s0
	s_and_b32 s1, s0, -8
	s_sub_i32 s1, s95, s1
	s_lshl_b32 s3, s1, 5
	s_ashr_i32 s0, s0, 3
	s_mul_i32 s2, s1, 33
	s_cmp_lt_i32 s1, 0
	s_cselect_b32 s1, s2, s3
	s_add_i32 s0, s1, s0
	s_ashr_i32 s1, s0, 31
	s_lshr_b32 s1, s1, 24
	s_add_i32 s1, s0, s1
	s_ashr_i32 s2, s1, 8
	s_and_b32 s1, s1, 0xffffff00
	s_sub_i32 s0, s0, s1
	s_sext_i32_i16 s1, s0
	s_bfe_u32 s1, s1, 0x3001c
	s_add_i32 s1, s0, s1
	s_sext_i32_i16 s3, s1
	s_and_b32 s1, s1, 0xfff8
	s_sub_i32 s0, s0, s1
	s_lshl_b32 s2, s2, 3
	s_sext_i32_i16 s0, s0
	s_add_i32 s88, s2, s0
	s_ashr_i32 s86, s3, 3

.LBB0_557:
	s_waitcnt vmcnt(0)
	s_waitcnt vmcnt(0)
	s_barrier
	v_readfirstlane_b32 vcc_lo, v252
	s_lshr_b32 vcc_lo, vcc_lo, 6
	s_cmp_lg_u32 vcc_lo, 1
	s_cbranch_scc1 .Lbar_noinv_4
	buffer_inv sc1
.Lbar_noinv_4:
	s_and_saveexec_b64 s[2:3], s[42:43]
	v_readlane_b32 s14, v254, 46
	v_readlane_b32 s20, v254, 34
	v_readlane_b32 s15, v254, 47
	v_readlane_b32 s21, v254, 35
	v_readlane_b32 s24, v254, 20
	v_readlane_b32 s25, v254, 21
	s_cbranch_execz .LBB0_609
	s_add_i32 s4, 0, 0x23fc0
	v_mov_b32_e32 v0, s4
	s_add_i32 s4, 0, 0x23fc4
	s_waitcnt vmcnt(0) expcnt(0) lgkmcnt(0)
	ds_read_b32 v2, v0
	v_mov_b32_e32 v0, s4
	s_add_i32 s4, 0, 0x23fc8
	v_mov_b32_e32 v1, s4
	ds_read_b32 v0, v0
	ds_read_b32 v1, v1
	s_waitcnt lgkmcnt(2)
	v_cmp_ne_u32_e32 vcc, 0, v2
	s_waitcnt lgkmcnt(0)
	v_readfirstlane_b32 s10, v1
	s_cbranch_vccnz .LBB0_573
	s_mov_b32 s11, 1
	v_mov_b32_e32 v16, 0
	s_branch .LBB0_561

.LBB0_609:
	s_or_b64 exec, exec, s[2:3]
	v_mov_b32_e32 v0, v252
	v_readlane_b32 s2, v254, 7
	s_waitcnt vmcnt(0) lgkmcnt(0)
	s_barrier
	s_nop 0
	v_add_u32_e32 v64, s2, v0
	s_mov_b32 s2, 0x20000
	v_cmp_gt_i32_e32 vcc, s2, v64
	s_and_saveexec_b64 s[2:3], vcc
	s_xor_b64 s[2:3], exec, s[2:3]
	s_cbranch_execz .LBB0_615
	v_lshrrev_b32_e32 v236, 16, v64
	v_lshrrev_b32_e32 v237, 14, v64
	v_and_b32_e32 v238, 0x3fff, v64
	v_lshlrev_b32_e32 v239, 23, v237
	v_lshl_add_u32 v239, v238, 2, v239
	v_and_b32_e32 v237, 3, v237
	v_lshlrev_b32_e32 v237, 9, v237
	v_lshl_add_u32 v237, v236, 18, v237
	v_and_b32_e32 v238, 63, v64
	v_lshl_add_u32 v240, v238, 3, v237
	v_mul_u32_u24_e32 v241, 0x7f0000, v236
	v_add_u32_e32 v239, v239, v241
	v_mul_u32_u24_e32 v241, 0x3f800, v236
	v_add_u32_e32 v240, v240, v241
	v_sub_u32_e32 v231, 0, v236
	v_mov_b32_e32 v233, v231
	v_lshlrev_b32_e32 v241, 17, v236
	v_sub_u32_e32 v230, 0x10000, v241
	v_lshlrev_b32_e32 v241, 12, v236
	v_sub_u32_e32 v232, 0x800, v241
	v_mov_b32_e32 v236, 0
	v_mov_b32_e32 v224, v239
	v_mov_b32_e32 v225, 0
	v_lshl_add_u64 v[224:225], s[40:41], 0, v[224:225]
	v_mov_b32_e32 v228, v240
	v_mov_b32_e32 v229, 0
	v_lshl_add_u64 v[228:229], s[12:13], 0, v[228:229]
	v_mov_b32_e32 v226, v224
	v_mov_b32_e32 v227, v225
	v_mov_b32_e32 v234, 0x7fff
	v_mov_b32_e32 v235, 0xffff0000
	v_mov_b32_e32 v218, 0
	v_mov_b32_e32 v219, 0

.LBB0_647:
	s_or_b64 exec, exec, s[2:3]
	v_mov_b32_e32 v111, v24
	s_waitcnt lgkmcnt(0)
	s_barrier
	s_nop 0
	v_cmp_gt_i32_e32 vcc, s95, v111
	s_and_saveexec_b64 s[2:3], vcc
	s_cbranch_execz .LBB0_650
	v_and_b32_e32 v0, 3, v111
	v_lshlrev_b32_e32 v2, 8, v0
	v_cvt_f32_u32_e32 v2, v2
	v_add_u32_e32 v25, 0xfffffe00, v111
	v_lshlrev_b32_e32 v111, 4, v111
	s_mov_b64 s[10:11], 0
	v_mul_f32_e32 v3, 0x38800000, v2
	v_cos_f32_e32 v2, v3
	v_sin_f32_e32 v20, v3
	v_lshlrev_b32_e32 v3, 9, v0
	v_cvt_f32_u32_e32 v3, v3
	v_mul_f32_e32 v22, 0xbf6c835e, v2
	v_mul_f32_e32 v30, 0xbec3ef15, v20
	v_mul_f32_e32 v32, 0x3ec3ef15, v2
	v_mul_f32_e32 v3, 0x38800000, v3
	v_cos_f32_e32 v54, v3
	v_sin_f32_e32 v56, v3
	v_lshlrev_b32_e32 v3, 10, v0
	v_cvt_f32_u32_e32 v3, v3
	v_mul_f32_e32 v34, 0xbf3504f3, v2
	v_mul_f32_e32 v36, 0xbf3504f3, v20
	v_mul_f32_e32 v46, 0xbf6c835e, v20
	v_mul_f32_e32 v3, 0x38800000, v3
	v_cos_f32_e32 v72, v3
	v_sin_f32_e32 v74, v3
	v_lshlrev_b32_e32 v3, 11, v0
	v_cvt_f32_u32_e32 v3, v3
	v_mul_f32_e32 v60, 0xbf3504f3, v54
	v_mul_f32_e32 v62, 0xbf3504f3, v56
	v_fmamk_f32 v38, v2, 0x3f6c835e, v30
	v_mul_f32_e32 v3, 0x38800000, v3
	v_cos_f32_e32 v80, v3
	v_sin_f32_e32 v82, v3
	v_fma_f32 v40, v20, s80, -v32
	v_fmamk_f32 v42, v2, 0x3f3504f3, v36
	v_fmamk_f32 v44, v20, 0xbf3504f3, v34
	v_fmamk_f32 v48, v20, 0xbec3ef15, v22
	v_fma_f32 v50, v2, 0, -v20
	v_fma_f32 v52, v20, s39, -v2
	v_fmac_f32_e32 v46, 0xbec3ef15, v2
	v_fmac_f32_e32 v22, 0x3ec3ef15, v20
	v_fmac_f32_e32 v36, 0xbf3504f3, v2
	v_fmac_f32_e32 v34, 0x3f3504f3, v20
	v_fmac_f32_e32 v30, 0xbf6c835e, v2
	v_fma_f32 v58, v20, s14, -v32
	v_fmac_f32_e32 v32, 0xbf6c835e, v20
	v_fmamk_f32 v64, v54, 0x3f3504f3, v62
	v_fmamk_f32 v66, v56, 0xbf3504f3, v60
	v_fma_f32 v68, v54, 0, -v56
	v_fma_f32 v70, v56, s39, -v54
	v_fmac_f32_e32 v62, 0xbf3504f3, v54
	v_fmac_f32_e32 v60, 0x3f3504f3, v56
	v_fma_f32 v76, v72, 0, -v74
	v_fma_f32 v78, v74, s39, -v72
	v_mov_b32_e32 v77, v76
	v_mov_b32_e32 v79, v78
	v_mov_b32_e32 v73, v72
	v_mov_b32_e32 v75, v74
	v_mov_b32_e32 v63, v62
	v_mov_b32_e32 v61, v60
	v_mov_b32_e32 v65, v64
	v_mov_b32_e32 v67, v66
	v_mov_b32_e32 v69, v68
	v_mov_b32_e32 v71, v70
	v_mov_b32_e32 v55, v54
	v_mov_b32_e32 v57, v56
	v_mov_b32_e32 v31, v30
	v_mov_b32_e32 v33, v32
	s_waitcnt vmcnt(0)
	global_load_dword v168, v[224:225], off
	global_load_dwordx2 v[186:187], v[228:229], off
	v_lshl_add_u64 v[224:225], v[224:225], 0, v[230:231]
	v_lshl_add_u64 v[228:229], v[228:229], 0, v[232:233]
	global_load_dword v169, v[224:225], off
	global_load_dwordx2 v[188:189], v[228:229], off
	v_lshl_add_u64 v[224:225], v[224:225], 0, v[230:231]
	v_lshl_add_u64 v[228:229], v[228:229], 0, v[232:233]
	global_load_dword v170, v[224:225], off
	global_load_dwordx2 v[190:191], v[228:229], off
	v_lshl_add_u64 v[224:225], v[224:225], 0, v[230:231]
	v_lshl_add_u64 v[228:229], v[228:229], 0, v[232:233]
	global_load_dword v171, v[224:225], off
	global_load_dwordx2 v[192:193], v[228:229], off
	v_lshl_add_u64 v[224:225], v[224:225], 0, v[230:231]
	v_lshl_add_u64 v[228:229], v[228:229], 0, v[232:233]
	global_load_dword v172, v[224:225], off
	global_load_dwordx2 v[194:195], v[228:229], off
	v_lshl_add_u64 v[224:225], v[224:225], 0, v[230:231]
	v_lshl_add_u64 v[228:229], v[228:229], 0, v[232:233]
	global_load_dword v173, v[224:225], off
	global_load_dwordx2 v[196:197], v[228:229], off
	v_lshl_add_u64 v[224:225], v[224:225], 0, v[230:231]
	v_lshl_add_u64 v[228:229], v[228:229], 0, v[232:233]
	global_load_dword v174, v[224:225], off
	global_load_dwordx2 v[198:199], v[228:229], off
	v_lshl_add_u64 v[224:225], v[224:225], 0, v[230:231]
	v_lshl_add_u64 v[228:229], v[228:229], 0, v[232:233]
	global_load_dword v175, v[224:225], off
	global_load_dwordx2 v[200:201], v[228:229], off
	v_lshl_add_u64 v[224:225], v[224:225], 0, v[230:231]
	v_lshl_add_u64 v[228:229], v[228:229], 0, v[232:233]
	global_load_dword v176, v[224:225], off
	global_load_dwordx2 v[202:203], v[228:229], off
	v_lshl_add_u64 v[224:225], v[224:225], 0, v[230:231]
	v_lshl_add_u64 v[228:229], v[228:229], 0, v[232:233]
	global_load_dword v177, v[224:225], off
	global_load_dwordx2 v[204:205], v[228:229], off
	v_lshl_add_u64 v[224:225], v[224:225], 0, v[230:231]
	v_lshl_add_u64 v[228:229], v[228:229], 0, v[232:233]
	global_load_dword v180, v[224:225], off
	global_load_dwordx2 v[206:207], v[228:229], off
	v_lshl_add_u64 v[224:225], v[224:225], 0, v[230:231]
	v_lshl_add_u64 v[228:229], v[228:229], 0, v[232:233]
	global_load_dword v181, v[224:225], off
	global_load_dwordx2 v[208:209], v[228:229], off
	v_lshl_add_u64 v[224:225], v[224:225], 0, v[230:231]
	v_lshl_add_u64 v[228:229], v[228:229], 0, v[232:233]
	global_load_dword v182, v[224:225], off
	global_load_dwordx2 v[210:211], v[228:229], off
	v_lshl_add_u64 v[224:225], v[224:225], 0, v[230:231]
	v_lshl_add_u64 v[228:229], v[228:229], 0, v[232:233]
	global_load_dword v183, v[224:225], off
	global_load_dwordx2 v[212:213], v[228:229], off
	v_lshl_add_u64 v[224:225], v[224:225], 0, v[230:231]
	v_lshl_add_u64 v[228:229], v[228:229], 0, v[232:233]
	global_load_dword v184, v[224:225], off
	global_load_dwordx2 v[214:215], v[228:229], off
	v_lshl_add_u64 v[224:225], v[224:225], 0, v[230:231]
	v_lshl_add_u64 v[228:229], v[228:229], 0, v[232:233]
	global_load_dword v185, v[224:225], off
	global_load_dwordx2 v[216:217], v[228:229], off
	v_lshl_add_u64 v[224:225], v[224:225], 0, v[230:231]
	v_lshl_add_u64 v[228:229], v[228:229], 0, v[232:233]
	v_mov_b32_e32 v37, v36
	v_mov_b32_e32 v43, v42
	v_mov_b32_e32 v47, v46
	v_mov_b32_e32 v39, v38
	v_mov_b32_e32 v51, v50
	v_mov_b32_e32 v3, v2
	v_mov_b32_e32 v81, v80
	v_mov_b32_e32 v83, v82
	v_mov_b32_e32 v21, v20
	v_mov_b32_e32 v41, v40
	v_mov_b32_e32 v45, v44
	v_mov_b32_e32 v49, v48
	v_mov_b32_e32 v53, v52
	v_mov_b32_e32 v23, v22
	v_mov_b32_e32 v35, v34
	v_mov_b32_e32 v59, v58

.LBB0_661:
	s_or_b64 exec, exec, s[2:3]
	s_or_b32 s10, s28, 1
	s_add_u32 s30, s16, s30
	s_addc_u32 s31, s17, s31
	v_lshl_add_u64 v[2:3], s[30:31], 0, v[28:29]
	s_ashr_i32 s11, s10, 31
	s_lshl_b64 s[2:3], s[10:11], 14
	v_add_co_u32_e32 v22, vcc, s47, v2
	s_add_u32 s86, s16, s2
	s_nop 0
	v_addc_co_u32_e32 v23, vcc, 0, v3, vcc
	s_addc_u32 s87, s17, s3
	v_add_co_u32_e32 v30, vcc, s79, v2
	v_lshl_add_u64 v[20:21], s[86:87], 0, v[28:29]
	s_nop 0
	v_addc_co_u32_e32 v31, vcc, 0, v3, vcc
	v_add_co_u32_e32 v32, vcc, s47, v20
	s_movk_i32 s2, 0x3000
	s_nop 0
	v_addc_co_u32_e32 v33, vcc, 0, v21, vcc
	v_add_co_u32_e32 v34, vcc, s79, v20
	s_nop 1
	v_addc_co_u32_e32 v35, vcc, 0, v21, vcc
	s_barrier
	global_load_ushort v0, v[2:3], off
	global_load_ushort v25, v[20:21], off
	global_load_ushort v36, v[2:3], off offset:1024
	global_load_ushort v37, v[20:21], off offset:1024
	global_load_ushort v38, v[2:3], off offset:2048
	global_load_ushort v39, v[20:21], off offset:2048
	global_load_ushort v41, v[20:21], off offset:3072
	global_load_ushort v42, v[2:3], off offset:3072
	v_add_co_u32_e32 v2, vcc, s2, v2
	global_load_ushort v40, v[22:23], off offset:1024
	global_load_ushort v43, v[22:23], off offset:2048
	global_load_ushort v44, v[30:31], off offset:-4096
	global_load_ushort v45, v[30:31], off
	global_load_ushort v46, v[34:35], off offset:-4096
	global_load_ushort v47, v[30:31], off offset:1024
	global_load_ushort v48, v[30:31], off offset:2048
	v_addc_co_u32_e32 v3, vcc, 0, v3, vcc
	v_add_co_u32_e32 v20, vcc, s2, v20
	global_load_ushort v49, v[32:33], off offset:1024
	global_load_ushort v50, v[32:33], off offset:2048
	global_load_ushort v51, v[32:33], off offset:3072
	global_load_ushort v52, v[2:3], off
	global_load_ushort v53, v[2:3], off offset:1024
	global_load_ushort v54, v[22:23], off offset:3072
	global_load_ushort v55, v[34:35], off
	global_load_ushort v56, v[34:35], off offset:1024
	global_load_ushort v57, v[34:35], off offset:2048
	global_load_ushort v58, v[34:35], off offset:3072
	global_load_ushort v59, v[30:31], off offset:3072
	v_addc_co_u32_e32 v21, vcc, 0, v21, vcc
	global_load_ushort v60, v[20:21], off
	global_load_ushort v61, v[20:21], off offset:1024
	global_load_ushort v62, v[2:3], off offset:2048
	global_load_ushort v63, v[20:21], off offset:2048
	global_load_ushort v64, v[20:21], off offset:3072
	global_load_ushort v65, v[2:3], off offset:3072
	s_waitcnt vmcnt(31)
	v_lshlrev_b32_e32 v2, 16, v0
	s_waitcnt vmcnt(30)
	v_lshlrev_b32_e32 v3, 16, v25
	v_mov_b32_e32 v25, v24
	s_waitcnt vmcnt(29)
	v_lshlrev_b32_e32 v20, 16, v36
	s_waitcnt vmcnt(27)
	v_lshlrev_b32_e32 v22, 16, v38
	s_waitcnt vmcnt(23)
	v_lshlrev_b32_e32 v32, 16, v40
	s_waitcnt vmcnt(21)
	v_lshlrev_b32_e32 v30, 16, v44
	v_lshlrev_b32_e32 v34, 16, v43
	s_waitcnt vmcnt(20)
	v_lshlrev_b32_e32 v36, 16, v45
	s_waitcnt vmcnt(18)
	v_lshlrev_b32_e32 v38, 16, v47
	s_waitcnt vmcnt(17)
	v_lshlrev_b32_e32 v40, 16, v48
	v_lshlrev_b32_e32 v21, 16, v37
	v_lshlrev_b32_e32 v23, 16, v39
	v_lshlrev_b32_e32 v42, 16, v42
	v_lshlrev_b32_e32 v43, 16, v41
	v_lshlrev_b32_e32 v31, 16, v46
	s_waitcnt vmcnt(16)
	v_lshlrev_b32_e32 v33, 16, v49
	s_waitcnt vmcnt(15)
	v_lshlrev_b32_e32 v35, 16, v50
	s_waitcnt vmcnt(11)
	v_lshlrev_b32_e32 v44, 16, v54
	v_lshlrev_b32_e32 v45, 16, v51
	s_waitcnt vmcnt(10)
	v_lshlrev_b32_e32 v37, 16, v55
	s_waitcnt vmcnt(9)
	v_lshlrev_b32_e32 v39, 16, v56
	s_waitcnt vmcnt(8)
	v_lshlrev_b32_e32 v41, 16, v57
	s_waitcnt vmcnt(6)
	v_lshlrev_b32_e32 v46, 16, v59
	v_lshlrev_b32_e32 v47, 16, v58
	v_lshlrev_b32_e32 v48, 16, v52
	s_waitcnt vmcnt(5)
	v_lshlrev_b32_e32 v49, 16, v60
	v_lshlrev_b32_e32 v50, 16, v53
	s_waitcnt vmcnt(4)
	v_lshlrev_b32_e32 v51, 16, v61
	s_waitcnt vmcnt(3)
	v_lshlrev_b32_e32 v52, 16, v62
	s_waitcnt vmcnt(2)
	v_lshlrev_b32_e32 v53, 16, v63
	s_waitcnt vmcnt(0)
	v_lshlrev_b32_e32 v54, 16, v65
	v_lshlrev_b32_e32 v55, 16, v64
	ds_write_b64 v91, v[2:3]
	ds_write_b64 v93, v[20:21] offset:4096
	ds_write_b64 v94, v[22:23] offset:8192
	ds_write_b64 v95, v[42:43] offset:12288
	ds_write_b64 v96, v[30:31] offset:16384
	ds_write_b64 v97, v[32:33] offset:20480
	ds_write_b64 v98, v[34:35] offset:24576
	ds_write_b64 v99, v[44:45] offset:28672
	ds_write_b64 v100, v[36:37] offset:32768
	ds_write_b64 v101, v[38:39] offset:36864
	ds_write_b64 v102, v[40:41] offset:40960
	ds_write_b64 v103, v[46:47] offset:45056
	ds_write_b64 v104, v[48:49] offset:49152
	ds_write_b64 v105, v[50:51] offset:53248
	ds_write_b64 v106, v[52:53] offset:57344
	ds_write_b64 v107, v[54:55] offset:61440
	s_waitcnt lgkmcnt(0)
	s_barrier
	s_waitcnt vmcnt(0)
	v_lshlrev_b32_e32 v220, 16, v168
	v_and_b32_e32 v221, 0xffff0000, v168
	v_bfe_u32 v222, v218, 16, 1
	v_bfe_u32 v223, v219, 16, 1
	v_add3_u32 v222, v218, v222, v234
	v_add3_u32 v223, v219, v223, v234
	v_lshrrev_b32_e32 v222, 16, v222
	v_and_or_b32 v222, v223, v235, v222
	global_store_dword v[226:227], v222, off
	v_pk_fma_f32 v[218:219], v[186:187], v[218:219], v[220:221]
	v_lshl_add_u64 v[226:227], v[226:227], 0, v[230:231]
	v_lshlrev_b32_e32 v220, 16, v169
	v_and_b32_e32 v221, 0xffff0000, v169
	v_bfe_u32 v222, v218, 16, 1
	v_bfe_u32 v223, v219, 16, 1
	v_add3_u32 v222, v218, v222, v234
	v_add3_u32 v223, v219, v223, v234
	v_lshrrev_b32_e32 v222, 16, v222
	v_and_or_b32 v222, v223, v235, v222
	global_store_dword v[226:227], v222, off
	v_pk_fma_f32 v[218:219], v[188:189], v[218:219], v[220:221]
	v_lshl_add_u64 v[226:227], v[226:227], 0, v[230:231]
	v_lshlrev_b32_e32 v220, 16, v170
	v_and_b32_e32 v221, 0xffff0000, v170
	v_bfe_u32 v222, v218, 16, 1
	v_bfe_u32 v223, v219, 16, 1
	v_add3_u32 v222, v218, v222, v234
	v_add3_u32 v223, v219, v223, v234
	v_lshrrev_b32_e32 v222, 16, v222
	v_and_or_b32 v222, v223, v235, v222
	global_store_dword v[226:227], v222, off
	v_pk_fma_f32 v[218:219], v[190:191], v[218:219], v[220:221]
	v_lshl_add_u64 v[226:227], v[226:227], 0, v[230:231]
	v_lshlrev_b32_e32 v220, 16, v171
	v_and_b32_e32 v221, 0xffff0000, v171
	v_bfe_u32 v222, v218, 16, 1
	v_bfe_u32 v223, v219, 16, 1
	v_add3_u32 v222, v218, v222, v234
	v_add3_u32 v223, v219, v223, v234
	v_lshrrev_b32_e32 v222, 16, v222
	v_and_or_b32 v222, v223, v235, v222
	global_store_dword v[226:227], v222, off
	v_pk_fma_f32 v[218:219], v[192:193], v[218:219], v[220:221]
	v_lshl_add_u64 v[226:227], v[226:227], 0, v[230:231]
	v_lshlrev_b32_e32 v220, 16, v172
	v_and_b32_e32 v221, 0xffff0000, v172
	v_bfe_u32 v222, v218, 16, 1
	v_bfe_u32 v223, v219, 16, 1
	v_add3_u32 v222, v218, v222, v234
	v_add3_u32 v223, v219, v223, v234
	v_lshrrev_b32_e32 v222, 16, v222
	v_and_or_b32 v222, v223, v235, v222
	global_store_dword v[226:227], v222, off
	v_pk_fma_f32 v[218:219], v[194:195], v[218:219], v[220:221]
	v_lshl_add_u64 v[226:227], v[226:227], 0, v[230:231]
	v_lshlrev_b32_e32 v220, 16, v173
	v_and_b32_e32 v221, 0xffff0000, v173
	v_bfe_u32 v222, v218, 16, 1
	v_bfe_u32 v223, v219, 16, 1
	v_add3_u32 v222, v218, v222, v234
	v_add3_u32 v223, v219, v223, v234
	v_lshrrev_b32_e32 v222, 16, v222
	v_and_or_b32 v222, v223, v235, v222
	global_store_dword v[226:227], v222, off
	v_pk_fma_f32 v[218:219], v[196:197], v[218:219], v[220:221]
	v_lshl_add_u64 v[226:227], v[226:227], 0, v[230:231]
	v_lshlrev_b32_e32 v220, 16, v174
	v_and_b32_e32 v221, 0xffff0000, v174
	v_bfe_u32 v222, v218, 16, 1
	v_bfe_u32 v223, v219, 16, 1
	v_add3_u32 v222, v218, v222, v234
	v_add3_u32 v223, v219, v223, v234
	v_lshrrev_b32_e32 v222, 16, v222
	v_and_or_b32 v222, v223, v235, v222
	global_store_dword v[226:227], v222, off
	v_pk_fma_f32 v[218:219], v[198:199], v[218:219], v[220:221]
	v_lshl_add_u64 v[226:227], v[226:227], 0, v[230:231]
	v_lshlrev_b32_e32 v220, 16, v175
	v_and_b32_e32 v221, 0xffff0000, v175
	v_bfe_u32 v222, v218, 16, 1
	v_bfe_u32 v223, v219, 16, 1
	v_add3_u32 v222, v218, v222, v234
	v_add3_u32 v223, v219, v223, v234
	v_lshrrev_b32_e32 v222, 16, v222
	v_and_or_b32 v222, v223, v235, v222
	global_store_dword v[226:227], v222, off
	v_pk_fma_f32 v[218:219], v[200:201], v[218:219], v[220:221]
	v_lshl_add_u64 v[226:227], v[226:227], 0, v[230:231]
	v_lshlrev_b32_e32 v220, 16, v176
	v_and_b32_e32 v221, 0xffff0000, v176
	v_bfe_u32 v222, v218, 16, 1
	v_bfe_u32 v223, v219, 16, 1
	v_add3_u32 v222, v218, v222, v234
	v_add3_u32 v223, v219, v223, v234
	v_lshrrev_b32_e32 v222, 16, v222
	v_and_or_b32 v222, v223, v235, v222
	global_store_dword v[226:227], v222, off
	v_pk_fma_f32 v[218:219], v[202:203], v[218:219], v[220:221]
	v_lshl_add_u64 v[226:227], v[226:227], 0, v[230:231]
	v_lshlrev_b32_e32 v220, 16, v177
	v_and_b32_e32 v221, 0xffff0000, v177
	v_bfe_u32 v222, v218, 16, 1
	v_bfe_u32 v223, v219, 16, 1
	v_add3_u32 v222, v218, v222, v234
	v_add3_u32 v223, v219, v223, v234
	v_lshrrev_b32_e32 v222, 16, v222
	v_and_or_b32 v222, v223, v235, v222
	global_store_dword v[226:227], v222, off
	v_pk_fma_f32 v[218:219], v[204:205], v[218:219], v[220:221]
	v_lshl_add_u64 v[226:227], v[226:227], 0, v[230:231]
	v_lshlrev_b32_e32 v220, 16, v180
	v_and_b32_e32 v221, 0xffff0000, v180
	v_bfe_u32 v222, v218, 16, 1
	v_bfe_u32 v223, v219, 16, 1
	v_add3_u32 v222, v218, v222, v234
	v_add3_u32 v223, v219, v223, v234
	v_lshrrev_b32_e32 v222, 16, v222
	v_and_or_b32 v222, v223, v235, v222
	global_store_dword v[226:227], v222, off
	v_pk_fma_f32 v[218:219], v[206:207], v[218:219], v[220:221]
	v_lshl_add_u64 v[226:227], v[226:227], 0, v[230:231]
	v_lshlrev_b32_e32 v220, 16, v181
	v_and_b32_e32 v221, 0xffff0000, v181
	v_bfe_u32 v222, v218, 16, 1
	v_bfe_u32 v223, v219, 16, 1
	v_add3_u32 v222, v218, v222, v234
	v_add3_u32 v223, v219, v223, v234
	v_lshrrev_b32_e32 v222, 16, v222
	v_and_or_b32 v222, v223, v235, v222
	global_store_dword v[226:227], v222, off
	v_pk_fma_f32 v[218:219], v[208:209], v[218:219], v[220:221]
	v_lshl_add_u64 v[226:227], v[226:227], 0, v[230:231]
	v_lshlrev_b32_e32 v220, 16, v182
	v_and_b32_e32 v221, 0xffff0000, v182
	v_bfe_u32 v222, v218, 16, 1
	v_bfe_u32 v223, v219, 16, 1
	v_add3_u32 v222, v218, v222, v234
	v_add3_u32 v223, v219, v223, v234
	v_lshrrev_b32_e32 v222, 16, v222
	v_and_or_b32 v222, v223, v235, v222
	global_store_dword v[226:227], v222, off
	v_pk_fma_f32 v[218:219], v[210:211], v[218:219], v[220:221]
	v_lshl_add_u64 v[226:227], v[226:227], 0, v[230:231]
	v_lshlrev_b32_e32 v220, 16, v183
	v_and_b32_e32 v221, 0xffff0000, v183
	v_bfe_u32 v222, v218, 16, 1
	v_bfe_u32 v223, v219, 16, 1
	v_add3_u32 v222, v218, v222, v234
	v_add3_u32 v223, v219, v223, v234
	v_lshrrev_b32_e32 v222, 16, v222
	v_and_or_b32 v222, v223, v235, v222
	global_store_dword v[226:227], v222, off
	v_pk_fma_f32 v[218:219], v[212:213], v[218:219], v[220:221]
	v_lshl_add_u64 v[226:227], v[226:227], 0, v[230:231]
	v_lshlrev_b32_e32 v220, 16, v184
	v_and_b32_e32 v221, 0xffff0000, v184
	v_bfe_u32 v222, v218, 16, 1
	v_bfe_u32 v223, v219, 16, 1
	v_add3_u32 v222, v218, v222, v234
	v_add3_u32 v223, v219, v223, v234
	v_lshrrev_b32_e32 v222, 16, v222
	v_and_or_b32 v222, v223, v235, v222
	global_store_dword v[226:227], v222, off
	v_pk_fma_f32 v[218:219], v[214:215], v[218:219], v[220:221]
	v_lshl_add_u64 v[226:227], v[226:227], 0, v[230:231]
	v_lshlrev_b32_e32 v220, 16, v185
	v_and_b32_e32 v221, 0xffff0000, v185
	v_bfe_u32 v222, v218, 16, 1
	v_bfe_u32 v223, v219, 16, 1
	v_add3_u32 v222, v218, v222, v234
	v_add3_u32 v223, v219, v223, v234
	v_lshrrev_b32_e32 v222, 16, v222
	v_and_or_b32 v222, v223, v235, v222
	global_store_dword v[226:227], v222, off
	v_pk_fma_f32 v[218:219], v[216:217], v[218:219], v[220:221]
	v_lshl_add_u64 v[226:227], v[226:227], 0, v[230:231]
	s_nop 0
	global_load_dword v168, v[224:225], off
	global_load_dwordx2 v[186:187], v[228:229], off
	v_lshl_add_u64 v[224:225], v[224:225], 0, v[230:231]
	v_lshl_add_u64 v[228:229], v[228:229], 0, v[232:233]
	global_load_dword v169, v[224:225], off
	global_load_dwordx2 v[188:189], v[228:229], off
	v_lshl_add_u64 v[224:225], v[224:225], 0, v[230:231]
	v_lshl_add_u64 v[228:229], v[228:229], 0, v[232:233]
	global_load_dword v170, v[224:225], off
	global_load_dwordx2 v[190:191], v[228:229], off
	v_lshl_add_u64 v[224:225], v[224:225], 0, v[230:231]
	v_lshl_add_u64 v[228:229], v[228:229], 0, v[232:233]
	global_load_dword v171, v[224:225], off
	global_load_dwordx2 v[192:193], v[228:229], off
	v_lshl_add_u64 v[224:225], v[224:225], 0, v[230:231]
	v_lshl_add_u64 v[228:229], v[228:229], 0, v[232:233]
	global_load_dword v172, v[224:225], off
	global_load_dwordx2 v[194:195], v[228:229], off
	v_lshl_add_u64 v[224:225], v[224:225], 0, v[230:231]
	v_lshl_add_u64 v[228:229], v[228:229], 0, v[232:233]
	global_load_dword v173, v[224:225], off
	global_load_dwordx2 v[196:197], v[228:229], off
	v_lshl_add_u64 v[224:225], v[224:225], 0, v[230:231]
	v_lshl_add_u64 v[228:229], v[228:229], 0, v[232:233]
	global_load_dword v174, v[224:225], off
	global_load_dwordx2 v[198:199], v[228:229], off
	v_lshl_add_u64 v[224:225], v[224:225], 0, v[230:231]
	v_lshl_add_u64 v[228:229], v[228:229], 0, v[232:233]
	global_load_dword v175, v[224:225], off
	global_load_dwordx2 v[200:201], v[228:229], off
	v_lshl_add_u64 v[224:225], v[224:225], 0, v[230:231]
	v_lshl_add_u64 v[228:229], v[228:229], 0, v[232:233]
	global_load_dword v176, v[224:225], off
	global_load_dwordx2 v[202:203], v[228:229], off
	v_lshl_add_u64 v[224:225], v[224:225], 0, v[230:231]
	v_lshl_add_u64 v[228:229], v[228:229], 0, v[232:233]
	global_load_dword v177, v[224:225], off
	global_load_dwordx2 v[204:205], v[228:229], off
	v_lshl_add_u64 v[224:225], v[224:225], 0, v[230:231]
	v_lshl_add_u64 v[228:229], v[228:229], 0, v[232:233]
	global_load_dword v180, v[224:225], off
	global_load_dwordx2 v[206:207], v[228:229], off
	v_lshl_add_u64 v[224:225], v[224:225], 0, v[230:231]
	v_lshl_add_u64 v[228:229], v[228:229], 0, v[232:233]
	global_load_dword v181, v[224:225], off
	global_load_dwordx2 v[208:209], v[228:229], off
	v_lshl_add_u64 v[224:225], v[224:225], 0, v[230:231]
	v_lshl_add_u64 v[228:229], v[228:229], 0, v[232:233]
	global_load_dword v182, v[224:225], off
	global_load_dwordx2 v[210:211], v[228:229], off
	v_lshl_add_u64 v[224:225], v[224:225], 0, v[230:231]
	v_lshl_add_u64 v[228:229], v[228:229], 0, v[232:233]
	global_load_dword v183, v[224:225], off
	global_load_dwordx2 v[212:213], v[228:229], off
	v_lshl_add_u64 v[224:225], v[224:225], 0, v[230:231]
	v_lshl_add_u64 v[228:229], v[228:229], 0, v[232:233]
	global_load_dword v184, v[224:225], off
	global_load_dwordx2 v[214:215], v[228:229], off
	v_lshl_add_u64 v[224:225], v[224:225], 0, v[230:231]
	v_lshl_add_u64 v[228:229], v[228:229], 0, v[232:233]
	global_load_dword v185, v[224:225], off
	global_load_dwordx2 v[216:217], v[228:229], off
	v_lshl_add_u64 v[224:225], v[224:225], 0, v[230:231]
	v_lshl_add_u64 v[228:229], v[228:229], 0, v[232:233]
	s_nop 0
	v_cmp_gt_i32_e32 vcc, s95, v25
	s_and_saveexec_b64 s[2:3], vcc
	s_cbranch_execz .LBB0_664
	v_lshlrev_b32_e32 v0, 4, v25
	s_mov_b64 s[12:13], 0

.LBB0_673:
	s_or_b64 exec, exec, s[2:3]
	s_waitcnt lgkmcnt(0)
	s_barrier
	s_waitcnt vmcnt(0)
	v_lshlrev_b32_e32 v220, 16, v168
	v_and_b32_e32 v221, 0xffff0000, v168
	v_bfe_u32 v222, v218, 16, 1
	v_bfe_u32 v223, v219, 16, 1
	v_add3_u32 v222, v218, v222, v234
	v_add3_u32 v223, v219, v223, v234
	v_lshrrev_b32_e32 v222, 16, v222
	v_and_or_b32 v222, v223, v235, v222
	global_store_dword v[226:227], v222, off
	v_pk_fma_f32 v[218:219], v[186:187], v[218:219], v[220:221]
	v_lshl_add_u64 v[226:227], v[226:227], 0, v[230:231]
	v_lshlrev_b32_e32 v220, 16, v169
	v_and_b32_e32 v221, 0xffff0000, v169
	v_bfe_u32 v222, v218, 16, 1
	v_bfe_u32 v223, v219, 16, 1
	v_add3_u32 v222, v218, v222, v234
	v_add3_u32 v223, v219, v223, v234
	v_lshrrev_b32_e32 v222, 16, v222
	v_and_or_b32 v222, v223, v235, v222
	global_store_dword v[226:227], v222, off
	v_pk_fma_f32 v[218:219], v[188:189], v[218:219], v[220:221]
	v_lshl_add_u64 v[226:227], v[226:227], 0, v[230:231]
	v_lshlrev_b32_e32 v220, 16, v170
	v_and_b32_e32 v221, 0xffff0000, v170
	v_bfe_u32 v222, v218, 16, 1
	v_bfe_u32 v223, v219, 16, 1
	v_add3_u32 v222, v218, v222, v234
	v_add3_u32 v223, v219, v223, v234
	v_lshrrev_b32_e32 v222, 16, v222
	v_and_or_b32 v222, v223, v235, v222
	global_store_dword v[226:227], v222, off
	v_pk_fma_f32 v[218:219], v[190:191], v[218:219], v[220:221]
	v_lshl_add_u64 v[226:227], v[226:227], 0, v[230:231]
	v_lshlrev_b32_e32 v220, 16, v171
	v_and_b32_e32 v221, 0xffff0000, v171
	v_bfe_u32 v222, v218, 16, 1
	v_bfe_u32 v223, v219, 16, 1
	v_add3_u32 v222, v218, v222, v234
	v_add3_u32 v223, v219, v223, v234
	v_lshrrev_b32_e32 v222, 16, v222
	v_and_or_b32 v222, v223, v235, v222
	global_store_dword v[226:227], v222, off
	v_pk_fma_f32 v[218:219], v[192:193], v[218:219], v[220:221]
	v_lshl_add_u64 v[226:227], v[226:227], 0, v[230:231]
	v_lshlrev_b32_e32 v220, 16, v172
	v_and_b32_e32 v221, 0xffff0000, v172
	v_bfe_u32 v222, v218, 16, 1
	v_bfe_u32 v223, v219, 16, 1
	v_add3_u32 v222, v218, v222, v234
	v_add3_u32 v223, v219, v223, v234
	v_lshrrev_b32_e32 v222, 16, v222
	v_and_or_b32 v222, v223, v235, v222
	global_store_dword v[226:227], v222, off
	v_pk_fma_f32 v[218:219], v[194:195], v[218:219], v[220:221]
	v_lshl_add_u64 v[226:227], v[226:227], 0, v[230:231]
	v_lshlrev_b32_e32 v220, 16, v173
	v_and_b32_e32 v221, 0xffff0000, v173
	v_bfe_u32 v222, v218, 16, 1
	v_bfe_u32 v223, v219, 16, 1
	v_add3_u32 v222, v218, v222, v234
	v_add3_u32 v223, v219, v223, v234
	v_lshrrev_b32_e32 v222, 16, v222
	v_and_or_b32 v222, v223, v235, v222
	global_store_dword v[226:227], v222, off
	v_pk_fma_f32 v[218:219], v[196:197], v[218:219], v[220:221]
	v_lshl_add_u64 v[226:227], v[226:227], 0, v[230:231]
	v_lshlrev_b32_e32 v220, 16, v174
	v_and_b32_e32 v221, 0xffff0000, v174
	v_bfe_u32 v222, v218, 16, 1
	v_bfe_u32 v223, v219, 16, 1
	v_add3_u32 v222, v218, v222, v234
	v_add3_u32 v223, v219, v223, v234
	v_lshrrev_b32_e32 v222, 16, v222
	v_and_or_b32 v222, v223, v235, v222
	global_store_dword v[226:227], v222, off
	v_pk_fma_f32 v[218:219], v[198:199], v[218:219], v[220:221]
	v_lshl_add_u64 v[226:227], v[226:227], 0, v[230:231]
	v_lshlrev_b32_e32 v220, 16, v175
	v_and_b32_e32 v221, 0xffff0000, v175
	v_bfe_u32 v222, v218, 16, 1
	v_bfe_u32 v223, v219, 16, 1
	v_add3_u32 v222, v218, v222, v234
	v_add3_u32 v223, v219, v223, v234
	v_lshrrev_b32_e32 v222, 16, v222
	v_and_or_b32 v222, v223, v235, v222
	global_store_dword v[226:227], v222, off
	v_pk_fma_f32 v[218:219], v[200:201], v[218:219], v[220:221]
	v_lshl_add_u64 v[226:227], v[226:227], 0, v[230:231]
	v_lshlrev_b32_e32 v220, 16, v176
	v_and_b32_e32 v221, 0xffff0000, v176
	v_bfe_u32 v222, v218, 16, 1
	v_bfe_u32 v223, v219, 16, 1
	v_add3_u32 v222, v218, v222, v234
	v_add3_u32 v223, v219, v223, v234
	v_lshrrev_b32_e32 v222, 16, v222
	v_and_or_b32 v222, v223, v235, v222
	global_store_dword v[226:227], v222, off
	v_pk_fma_f32 v[218:219], v[202:203], v[218:219], v[220:221]
	v_lshl_add_u64 v[226:227], v[226:227], 0, v[230:231]
	v_lshlrev_b32_e32 v220, 16, v177
	v_and_b32_e32 v221, 0xffff0000, v177
	v_bfe_u32 v222, v218, 16, 1
	v_bfe_u32 v223, v219, 16, 1
	v_add3_u32 v222, v218, v222, v234
	v_add3_u32 v223, v219, v223, v234
	v_lshrrev_b32_e32 v222, 16, v222
	v_and_or_b32 v222, v223, v235, v222
	global_store_dword v[226:227], v222, off
	v_pk_fma_f32 v[218:219], v[204:205], v[218:219], v[220:221]
	v_lshl_add_u64 v[226:227], v[226:227], 0, v[230:231]
	v_lshlrev_b32_e32 v220, 16, v180
	v_and_b32_e32 v221, 0xffff0000, v180
	v_bfe_u32 v222, v218, 16, 1
	v_bfe_u32 v223, v219, 16, 1
	v_add3_u32 v222, v218, v222, v234
	v_add3_u32 v223, v219, v223, v234
	v_lshrrev_b32_e32 v222, 16, v222
	v_and_or_b32 v222, v223, v235, v222
	global_store_dword v[226:227], v222, off
	v_pk_fma_f32 v[218:219], v[206:207], v[218:219], v[220:221]
	v_lshl_add_u64 v[226:227], v[226:227], 0, v[230:231]
	v_lshlrev_b32_e32 v220, 16, v181
	v_and_b32_e32 v221, 0xffff0000, v181
	v_bfe_u32 v222, v218, 16, 1
	v_bfe_u32 v223, v219, 16, 1
	v_add3_u32 v222, v218, v222, v234
	v_add3_u32 v223, v219, v223, v234
	v_lshrrev_b32_e32 v222, 16, v222
	v_and_or_b32 v222, v223, v235, v222
	global_store_dword v[226:227], v222, off
	v_pk_fma_f32 v[218:219], v[208:209], v[218:219], v[220:221]
	v_lshl_add_u64 v[226:227], v[226:227], 0, v[230:231]
	v_lshlrev_b32_e32 v220, 16, v182
	v_and_b32_e32 v221, 0xffff0000, v182
	v_bfe_u32 v222, v218, 16, 1
	v_bfe_u32 v223, v219, 16, 1
	v_add3_u32 v222, v218, v222, v234
	v_add3_u32 v223, v219, v223, v234
	v_lshrrev_b32_e32 v222, 16, v222
	v_and_or_b32 v222, v223, v235, v222
	global_store_dword v[226:227], v222, off
	v_pk_fma_f32 v[218:219], v[210:211], v[218:219], v[220:221]
	v_lshl_add_u64 v[226:227], v[226:227], 0, v[230:231]
	v_lshlrev_b32_e32 v220, 16, v183
	v_and_b32_e32 v221, 0xffff0000, v183
	v_bfe_u32 v222, v218, 16, 1
	v_bfe_u32 v223, v219, 16, 1
	v_add3_u32 v222, v218, v222, v234
	v_add3_u32 v223, v219, v223, v234
	v_lshrrev_b32_e32 v222, 16, v222
	v_and_or_b32 v222, v223, v235, v222
	global_store_dword v[226:227], v222, off
	v_pk_fma_f32 v[218:219], v[212:213], v[218:219], v[220:221]
	v_lshl_add_u64 v[226:227], v[226:227], 0, v[230:231]
	v_lshlrev_b32_e32 v220, 16, v184
	v_and_b32_e32 v221, 0xffff0000, v184
	v_bfe_u32 v222, v218, 16, 1
	v_bfe_u32 v223, v219, 16, 1
	v_add3_u32 v222, v218, v222, v234
	v_add3_u32 v223, v219, v223, v234
	v_lshrrev_b32_e32 v222, 16, v222
	v_and_or_b32 v222, v223, v235, v222
	global_store_dword v[226:227], v222, off
	v_pk_fma_f32 v[218:219], v[214:215], v[218:219], v[220:221]
	v_lshl_add_u64 v[226:227], v[226:227], 0, v[230:231]
	v_lshlrev_b32_e32 v220, 16, v185
	v_and_b32_e32 v221, 0xffff0000, v185
	v_bfe_u32 v222, v218, 16, 1
	v_bfe_u32 v223, v219, 16, 1
	v_add3_u32 v222, v218, v222, v234
	v_add3_u32 v223, v219, v223, v234
	v_lshrrev_b32_e32 v222, 16, v222
	v_and_or_b32 v222, v223, v235, v222
	global_store_dword v[226:227], v222, off
	v_pk_fma_f32 v[218:219], v[216:217], v[218:219], v[220:221]
	v_lshl_add_u64 v[226:227], v[226:227], 0, v[230:231]
	s_nop 0
	s_and_saveexec_b64 s[2:3], s[4:5]
	s_cbranch_execz .LBB0_691
	v_mov_b32_e32 v2, v24
	s_mov_b64 s[12:13], exec
	v_readlane_b32 s20, v253, 7
	v_readlane_b32 s21, v253, 8
	s_and_b64 s[20:21], s[12:13], s[20:21]
	s_mov_b64 exec, s[20:21]
	s_cbranch_execz .LBB0_680
	global_load_dwordx4 v[20:23], v[26:27], off
	s_mov_b64 s[20:21], exec
	v_readlane_b32 s22, v254, 7
	v_readlane_b32 s23, v254, 8
	s_and_b64 s[22:23], s[20:21], s[22:23]
	s_xor_b64 s[82:83], s[22:23], s[20:21]
	s_mov_b64 exec, s[22:23]
	s_cbranch_execz .LBB0_677
	ds_read_b64 v[2:3], v108
	ds_read_b64 v[30:31], v110
	s_mov_b32 s20, s49
	s_mov_b32 s21, s48
	s_waitcnt vmcnt(0)
	v_mov_b32_e32 v38, v21
	v_mov_b32_e32 v39, v23
	s_waitcnt lgkmcnt(0)
	v_pk_add_f32 v[32:33], v[2:3], v[30:31]
	v_pk_add_f32 v[2:3], v[2:3], v[30:31] neg_lo:[0,1] neg_hi:[0,1]
	v_pk_mul_f32 v[30:31], v[32:33], 0.5 op_sel_hi:[1,0]
	v_pk_mul_f32 v[36:37], v[2:3], s[20:21]
	v_mov_b32_e32 v34, v33
	v_mov_b32_e32 v35, v3
	v_mov_b32_e32 v3, v32
	v_mov_b32_e32 v32, v20
	v_mov_b32_e32 v33, v22
	v_pk_mul_f32 v[36:37], v[38:39], v[36:37] op_sel:[0,1] op_sel_hi:[1,0]
	v_pk_mul_f32 v[34:35], v[34:35], 0.5 op_sel_hi:[1,0]
	v_pk_fma_f32 v[30:31], v[32:33], v[30:31], v[36:37] neg_lo:[0,0,1] neg_hi:[0,0,1]
	v_mov_b32_e32 v32, v23
	v_mov_b32_e32 v33, v20
	v_pk_mul_f32 v[2:3], v[2:3], s[20:21]
	v_pk_mul_f32 v[32:33], v[32:33], v[34:35]
	v_mov_b32_e32 v23, v21
	v_pk_fma_f32 v[2:3], v[22:23], v[2:3], v[32:33]
	s_nop 0
	v_pk_add_f32 v[20:21], v[30:31], v[2:3] neg_lo:[0,1] neg_hi:[0,1]
	v_pk_add_f32 v[2:3], v[30:31], v[2:3]
	v_mov_b32_e32 v22, v20
	v_mov_b32_e32 v23, v3
	v_mov_b32_e32 v3, v21
	ds_write_b64 v108, v[22:23]
	ds_write_b64 v110, v[2:3]

.LBB0_694:
	s_or_b64 exec, exec, s[2:3]
	v_mov_b32_e32 v111, v24
	s_waitcnt lgkmcnt(0)
	s_barrier
	s_nop 0
	v_cmp_gt_i32_e32 vcc, s95, v111
	s_and_saveexec_b64 s[2:3], vcc
	s_cbranch_execz .LBB0_697
	v_and_b32_e32 v0, 3, v111
	v_lshlrev_b32_e32 v3, 10, v0
	v_cvt_f32_u32_e32 v3, v3
	s_waitcnt vmcnt(0)
	global_load_dword v168, v[224:225], off
	global_load_dwordx2 v[186:187], v[228:229], off
	v_lshl_add_u64 v[224:225], v[224:225], 0, v[230:231]
	v_lshl_add_u64 v[228:229], v[228:229], 0, v[232:233]
	global_load_dword v169, v[224:225], off
	global_load_dwordx2 v[188:189], v[228:229], off
	v_lshl_add_u64 v[224:225], v[224:225], 0, v[230:231]
	v_lshl_add_u64 v[228:229], v[228:229], 0, v[232:233]
	global_load_dword v170, v[224:225], off
	global_load_dwordx2 v[190:191], v[228:229], off
	v_lshl_add_u64 v[224:225], v[224:225], 0, v[230:231]
	v_lshl_add_u64 v[228:229], v[228:229], 0, v[232:233]
	global_load_dword v171, v[224:225], off
	global_load_dwordx2 v[192:193], v[228:229], off
	v_lshl_add_u64 v[224:225], v[224:225], 0, v[230:231]
	v_lshl_add_u64 v[228:229], v[228:229], 0, v[232:233]
	global_load_dword v172, v[224:225], off
	global_load_dwordx2 v[194:195], v[228:229], off
	v_lshl_add_u64 v[224:225], v[224:225], 0, v[230:231]
	v_lshl_add_u64 v[228:229], v[228:229], 0, v[232:233]
	global_load_dword v173, v[224:225], off
	global_load_dwordx2 v[196:197], v[228:229], off
	v_lshl_add_u64 v[224:225], v[224:225], 0, v[230:231]
	v_lshl_add_u64 v[228:229], v[228:229], 0, v[232:233]
	global_load_dword v174, v[224:225], off
	global_load_dwordx2 v[198:199], v[228:229], off
	v_lshl_add_u64 v[224:225], v[224:225], 0, v[230:231]
	v_lshl_add_u64 v[228:229], v[228:229], 0, v[232:233]
	global_load_dword v175, v[224:225], off
	global_load_dwordx2 v[200:201], v[228:229], off
	v_lshl_add_u64 v[224:225], v[224:225], 0, v[230:231]
	v_lshl_add_u64 v[228:229], v[228:229], 0, v[232:233]
	global_load_dword v176, v[224:225], off
	global_load_dwordx2 v[202:203], v[228:229], off
	v_lshl_add_u64 v[224:225], v[224:225], 0, v[230:231]
	v_lshl_add_u64 v[228:229], v[228:229], 0, v[232:233]
	global_load_dword v177, v[224:225], off
	global_load_dwordx2 v[204:205], v[228:229], off
	v_lshl_add_u64 v[224:225], v[224:225], 0, v[230:231]
	v_lshl_add_u64 v[228:229], v[228:229], 0, v[232:233]
	global_load_dword v180, v[224:225], off
	global_load_dwordx2 v[206:207], v[228:229], off
	v_lshl_add_u64 v[224:225], v[224:225], 0, v[230:231]
	v_lshl_add_u64 v[228:229], v[228:229], 0, v[232:233]
	global_load_dword v181, v[224:225], off
	global_load_dwordx2 v[208:209], v[228:229], off
	v_lshl_add_u64 v[224:225], v[224:225], 0, v[230:231]
	v_lshl_add_u64 v[228:229], v[228:229], 0, v[232:233]
	global_load_dword v182, v[224:225], off
	global_load_dwordx2 v[210:211], v[228:229], off
	v_lshl_add_u64 v[224:225], v[224:225], 0, v[230:231]
	v_lshl_add_u64 v[228:229], v[228:229], 0, v[232:233]
	global_load_dword v183, v[224:225], off
	global_load_dwordx2 v[212:213], v[228:229], off
	v_lshl_add_u64 v[224:225], v[224:225], 0, v[230:231]
	v_lshl_add_u64 v[228:229], v[228:229], 0, v[232:233]
	global_load_dword v184, v[224:225], off
	global_load_dwordx2 v[214:215], v[228:229], off
	v_lshl_add_u64 v[224:225], v[224:225], 0, v[230:231]
	v_lshl_add_u64 v[228:229], v[228:229], 0, v[232:233]
	global_load_dword v185, v[224:225], off
	global_load_dwordx2 v[216:217], v[228:229], off
	v_lshl_add_u64 v[224:225], v[224:225], 0, v[230:231]
	v_lshl_add_u64 v[228:229], v[228:229], 0, v[232:233]
	v_lshlrev_b32_e32 v21, 9, v0
	v_cvt_f32_u32_e32 v21, v21
	v_lshlrev_b32_e32 v2, 11, v0
	v_mul_f32_e32 v3, 0x38800000, v3
	v_cos_f32_e32 v22, v3
	v_sin_f32_e32 v30, v3
	v_mul_f32_e32 v3, 0x38800000, v21
	v_cos_f32_e32 v32, v3
	v_sin_f32_e32 v34, v3
	v_lshlrev_b32_e32 v3, 8, v0
	v_cvt_f32_u32_e32 v3, v3
	v_cvt_f32_u32_e32 v2, v2
	v_mul_f32_e32 v40, 0xbf3504f3, v32
	v_mul_f32_e32 v42, 0xbf3504f3, v34
	v_mul_f32_e32 v3, 0x38800000, v3
	v_cos_f32_e32 v52, v3
	v_sin_f32_e32 v54, v3
	v_mul_f32_e32 v20, 0x38800000, v2
	v_cos_f32_e32 v2, v20
	v_sin_f32_e32 v20, v20
	v_mul_f32_e32 v56, 0xbf6c835e, v52
	v_mul_f32_e32 v58, 0xbec3ef15, v54
	v_mul_f32_e32 v62, 0x3ec3ef15, v52
	v_mul_f32_e32 v66, 0xbf3504f3, v52
	v_mul_f32_e32 v68, 0xbf3504f3, v54
	v_mul_f32_e32 v74, 0xbf6c835e, v54
	v_fma_f32 v36, v22, 0, -v30
	v_fma_f32 v38, v30, s39, -v22
	v_fmamk_f32 v44, v32, 0x3f3504f3, v42
	v_fmamk_f32 v46, v34, 0xbf3504f3, v40
	v_fma_f32 v48, v32, 0, -v34
	v_fma_f32 v50, v34, s39, -v32
	v_fmac_f32_e32 v42, 0xbf3504f3, v32
	v_fmac_f32_e32 v40, 0x3f3504f3, v34
	v_fmamk_f32 v60, v52, 0x3f6c835e, v58
	v_fma_f32 v64, v54, s80, -v62
	v_fmamk_f32 v70, v52, 0x3f3504f3, v68
	v_fmamk_f32 v72, v54, 0xbf3504f3, v66
	v_fmamk_f32 v76, v54, 0xbec3ef15, v56
	v_fma_f32 v78, v52, 0, -v54
	v_fma_f32 v80, v54, s39, -v52
	v_fmac_f32_e32 v74, 0xbec3ef15, v52
	v_fmac_f32_e32 v56, 0x3ec3ef15, v54
	v_fmac_f32_e32 v68, 0xbf3504f3, v52
	v_fmac_f32_e32 v66, 0x3f3504f3, v54
	v_fmac_f32_e32 v58, 0xbf6c835e, v52
	v_fma_f32 v82, v54, s14, -v62
	v_fmac_f32_e32 v62, 0xbf6c835e, v54
	v_mov_b32_e32 v59, v58
	v_mov_b32_e32 v69, v68
	v_mov_b32_e32 v75, v74
	v_mov_b32_e32 v79, v78
	v_mov_b32_e32 v63, v62
	v_mov_b32_e32 v71, v70
	v_mov_b32_e32 v61, v60
	v_mov_b32_e32 v53, v52
	v_mov_b32_e32 v43, v42
	v_mov_b32_e32 v41, v40
	v_mov_b32_e32 v49, v48
	v_mov_b32_e32 v51, v50
	v_mov_b32_e32 v45, v44
	v_mov_b32_e32 v47, v46
	v_mov_b32_e32 v33, v32
	v_mov_b32_e32 v35, v34
	v_mov_b32_e32 v37, v36
	v_mov_b32_e32 v39, v38
	v_mov_b32_e32 v23, v22
	v_mov_b32_e32 v31, v30
	v_mov_b32_e32 v3, v2
	v_mov_b32_e32 v21, v20
	v_mov_b32_e32 v55, v54
	v_mov_b32_e32 v65, v64
	v_mov_b32_e32 v73, v72
	v_mov_b32_e32 v77, v76
	v_mov_b32_e32 v81, v80
	v_mov_b32_e32 v57, v56
	v_mov_b32_e32 v67, v66
	v_mov_b32_e32 v83, v82
	v_add_u32_e32 v25, 0xfffffe00, v111
	v_lshlrev_b32_e32 v111, 4, v111
	s_mov_b64 s[12:13], 0

.LBB0_697:
	s_or_b64 exec, exec, s[2:3]
	v_mov_b32_e32 v111, v24
	s_waitcnt lgkmcnt(0)
	s_barrier
	s_nop 0
	v_cmp_gt_i32_e32 vcc, s95, v111
	s_and_saveexec_b64 s[2:3], vcc
	s_cbranch_execz .LBB0_700
	v_and_b32_e32 v0, 63, v111
	v_lshlrev_b32_e32 v3, 6, v0
	v_cvt_f32_u32_e32 v3, v3
	s_waitcnt vmcnt(0)
	s_waitcnt vmcnt(0)
	v_lshlrev_b32_e32 v220, 16, v168
	v_and_b32_e32 v221, 0xffff0000, v168
	v_bfe_u32 v222, v218, 16, 1
	v_bfe_u32 v223, v219, 16, 1
	v_add3_u32 v222, v218, v222, v234
	v_add3_u32 v223, v219, v223, v234
	v_lshrrev_b32_e32 v222, 16, v222
	v_and_or_b32 v222, v223, v235, v222
	global_store_dword v[226:227], v222, off
	v_pk_fma_f32 v[218:219], v[186:187], v[218:219], v[220:221]
	v_lshl_add_u64 v[226:227], v[226:227], 0, v[230:231]
	v_lshlrev_b32_e32 v220, 16, v169
	v_and_b32_e32 v221, 0xffff0000, v169
	v_bfe_u32 v222, v218, 16, 1
	v_bfe_u32 v223, v219, 16, 1
	v_add3_u32 v222, v218, v222, v234
	v_add3_u32 v223, v219, v223, v234
	v_lshrrev_b32_e32 v222, 16, v222
	v_and_or_b32 v222, v223, v235, v222
	global_store_dword v[226:227], v222, off
	v_pk_fma_f32 v[218:219], v[188:189], v[218:219], v[220:221]
	v_lshl_add_u64 v[226:227], v[226:227], 0, v[230:231]
	v_lshlrev_b32_e32 v220, 16, v170
	v_and_b32_e32 v221, 0xffff0000, v170
	v_bfe_u32 v222, v218, 16, 1
	v_bfe_u32 v223, v219, 16, 1
	v_add3_u32 v222, v218, v222, v234
	v_add3_u32 v223, v219, v223, v234
	v_lshrrev_b32_e32 v222, 16, v222
	v_and_or_b32 v222, v223, v235, v222
	global_store_dword v[226:227], v222, off
	v_pk_fma_f32 v[218:219], v[190:191], v[218:219], v[220:221]
	v_lshl_add_u64 v[226:227], v[226:227], 0, v[230:231]
	v_lshlrev_b32_e32 v220, 16, v171
	v_and_b32_e32 v221, 0xffff0000, v171
	v_bfe_u32 v222, v218, 16, 1
	v_bfe_u32 v223, v219, 16, 1
	v_add3_u32 v222, v218, v222, v234
	v_add3_u32 v223, v219, v223, v234
	v_lshrrev_b32_e32 v222, 16, v222
	v_and_or_b32 v222, v223, v235, v222
	global_store_dword v[226:227], v222, off
	v_pk_fma_f32 v[218:219], v[192:193], v[218:219], v[220:221]
	v_lshl_add_u64 v[226:227], v[226:227], 0, v[230:231]
	v_lshlrev_b32_e32 v220, 16, v172
	v_and_b32_e32 v221, 0xffff0000, v172
	v_bfe_u32 v222, v218, 16, 1
	v_bfe_u32 v223, v219, 16, 1
	v_add3_u32 v222, v218, v222, v234
	v_add3_u32 v223, v219, v223, v234
	v_lshrrev_b32_e32 v222, 16, v222
	v_and_or_b32 v222, v223, v235, v222
	global_store_dword v[226:227], v222, off
	v_pk_fma_f32 v[218:219], v[194:195], v[218:219], v[220:221]
	v_lshl_add_u64 v[226:227], v[226:227], 0, v[230:231]
	v_lshlrev_b32_e32 v220, 16, v173
	v_and_b32_e32 v221, 0xffff0000, v173
	v_bfe_u32 v222, v218, 16, 1
	v_bfe_u32 v223, v219, 16, 1
	v_add3_u32 v222, v218, v222, v234
	v_add3_u32 v223, v219, v223, v234
	v_lshrrev_b32_e32 v222, 16, v222
	v_and_or_b32 v222, v223, v235, v222
	global_store_dword v[226:227], v222, off
	v_pk_fma_f32 v[218:219], v[196:197], v[218:219], v[220:221]
	v_lshl_add_u64 v[226:227], v[226:227], 0, v[230:231]
	v_lshlrev_b32_e32 v220, 16, v174
	v_and_b32_e32 v221, 0xffff0000, v174
	v_bfe_u32 v222, v218, 16, 1
	v_bfe_u32 v223, v219, 16, 1
	v_add3_u32 v222, v218, v222, v234
	v_add3_u32 v223, v219, v223, v234
	v_lshrrev_b32_e32 v222, 16, v222
	v_and_or_b32 v222, v223, v235, v222
	global_store_dword v[226:227], v222, off
	v_pk_fma_f32 v[218:219], v[198:199], v[218:219], v[220:221]
	v_lshl_add_u64 v[226:227], v[226:227], 0, v[230:231]
	v_lshlrev_b32_e32 v220, 16, v175
	v_and_b32_e32 v221, 0xffff0000, v175
	v_bfe_u32 v222, v218, 16, 1
	v_bfe_u32 v223, v219, 16, 1
	v_add3_u32 v222, v218, v222, v234
	v_add3_u32 v223, v219, v223, v234
	v_lshrrev_b32_e32 v222, 16, v222
	v_and_or_b32 v222, v223, v235, v222
	global_store_dword v[226:227], v222, off
	v_pk_fma_f32 v[218:219], v[200:201], v[218:219], v[220:221]
	v_lshl_add_u64 v[226:227], v[226:227], 0, v[230:231]
	v_lshlrev_b32_e32 v220, 16, v176
	v_and_b32_e32 v221, 0xffff0000, v176
	v_bfe_u32 v222, v218, 16, 1
	v_bfe_u32 v223, v219, 16, 1
	v_add3_u32 v222, v218, v222, v234
	v_add3_u32 v223, v219, v223, v234
	v_lshrrev_b32_e32 v222, 16, v222
	v_and_or_b32 v222, v223, v235, v222
	global_store_dword v[226:227], v222, off
	v_pk_fma_f32 v[218:219], v[202:203], v[218:219], v[220:221]
	v_lshl_add_u64 v[226:227], v[226:227], 0, v[230:231]
	v_lshlrev_b32_e32 v220, 16, v177
	v_and_b32_e32 v221, 0xffff0000, v177
	v_bfe_u32 v222, v218, 16, 1
	v_bfe_u32 v223, v219, 16, 1
	v_add3_u32 v222, v218, v222, v234
	v_add3_u32 v223, v219, v223, v234
	v_lshrrev_b32_e32 v222, 16, v222
	v_and_or_b32 v222, v223, v235, v222
	global_store_dword v[226:227], v222, off
	v_pk_fma_f32 v[218:219], v[204:205], v[218:219], v[220:221]
	v_lshl_add_u64 v[226:227], v[226:227], 0, v[230:231]
	v_lshlrev_b32_e32 v220, 16, v180
	v_and_b32_e32 v221, 0xffff0000, v180
	v_bfe_u32 v222, v218, 16, 1
	v_bfe_u32 v223, v219, 16, 1
	v_add3_u32 v222, v218, v222, v234
	v_add3_u32 v223, v219, v223, v234
	v_lshrrev_b32_e32 v222, 16, v222
	v_and_or_b32 v222, v223, v235, v222
	global_store_dword v[226:227], v222, off
	v_pk_fma_f32 v[218:219], v[206:207], v[218:219], v[220:221]
	v_lshl_add_u64 v[226:227], v[226:227], 0, v[230:231]
	v_lshlrev_b32_e32 v220, 16, v181
	v_and_b32_e32 v221, 0xffff0000, v181
	v_bfe_u32 v222, v218, 16, 1
	v_bfe_u32 v223, v219, 16, 1
	v_add3_u32 v222, v218, v222, v234
	v_add3_u32 v223, v219, v223, v234
	v_lshrrev_b32_e32 v222, 16, v222
	v_and_or_b32 v222, v223, v235, v222
	global_store_dword v[226:227], v222, off
	v_pk_fma_f32 v[218:219], v[208:209], v[218:219], v[220:221]
	v_lshl_add_u64 v[226:227], v[226:227], 0, v[230:231]
	v_lshlrev_b32_e32 v220, 16, v182
	v_and_b32_e32 v221, 0xffff0000, v182
	v_bfe_u32 v222, v218, 16, 1
	v_bfe_u32 v223, v219, 16, 1
	v_add3_u32 v222, v218, v222, v234
	v_add3_u32 v223, v219, v223, v234
	v_lshrrev_b32_e32 v222, 16, v222
	v_and_or_b32 v222, v223, v235, v222
	global_store_dword v[226:227], v222, off
	v_pk_fma_f32 v[218:219], v[210:211], v[218:219], v[220:221]
	v_lshl_add_u64 v[226:227], v[226:227], 0, v[230:231]
	v_lshlrev_b32_e32 v220, 16, v183
	v_and_b32_e32 v221, 0xffff0000, v183
	v_bfe_u32 v222, v218, 16, 1
	v_bfe_u32 v223, v219, 16, 1
	v_add3_u32 v222, v218, v222, v234
	v_add3_u32 v223, v219, v223, v234
	v_lshrrev_b32_e32 v222, 16, v222
	v_and_or_b32 v222, v223, v235, v222
	global_store_dword v[226:227], v222, off
	v_pk_fma_f32 v[218:219], v[212:213], v[218:219], v[220:221]
	v_lshl_add_u64 v[226:227], v[226:227], 0, v[230:231]
	v_lshlrev_b32_e32 v220, 16, v184
	v_and_b32_e32 v221, 0xffff0000, v184
	v_bfe_u32 v222, v218, 16, 1
	v_bfe_u32 v223, v219, 16, 1
	v_add3_u32 v222, v218, v222, v234
	v_add3_u32 v223, v219, v223, v234
	v_lshrrev_b32_e32 v222, 16, v222
	v_and_or_b32 v222, v223, v235, v222
	global_store_dword v[226:227], v222, off
	v_pk_fma_f32 v[218:219], v[214:215], v[218:219], v[220:221]
	v_lshl_add_u64 v[226:227], v[226:227], 0, v[230:231]
	v_lshlrev_b32_e32 v220, 16, v185
	v_and_b32_e32 v221, 0xffff0000, v185
	v_bfe_u32 v222, v218, 16, 1
	v_bfe_u32 v223, v219, 16, 1
	v_add3_u32 v222, v218, v222, v234
	v_add3_u32 v223, v219, v223, v234
	v_lshrrev_b32_e32 v222, 16, v222
	v_and_or_b32 v222, v223, v235, v222
	global_store_dword v[226:227], v222, off
	v_pk_fma_f32 v[218:219], v[216:217], v[218:219], v[220:221]
	v_lshl_add_u64 v[226:227], v[226:227], 0, v[230:231]
	s_nop 0
	global_load_dword v168, v[224:225], off
	global_load_dwordx2 v[186:187], v[228:229], off
	v_lshl_add_u64 v[224:225], v[224:225], 0, v[230:231]
	v_lshl_add_u64 v[228:229], v[228:229], 0, v[232:233]
	global_load_dword v169, v[224:225], off
	global_load_dwordx2 v[188:189], v[228:229], off
	v_lshl_add_u64 v[224:225], v[224:225], 0, v[230:231]
	v_lshl_add_u64 v[228:229], v[228:229], 0, v[232:233]
	global_load_dword v170, v[224:225], off
	global_load_dwordx2 v[190:191], v[228:229], off
	v_lshl_add_u64 v[224:225], v[224:225], 0, v[230:231]
	v_lshl_add_u64 v[228:229], v[228:229], 0, v[232:233]
	global_load_dword v171, v[224:225], off
	global_load_dwordx2 v[192:193], v[228:229], off
	v_lshl_add_u64 v[224:225], v[224:225], 0, v[230:231]
	v_lshl_add_u64 v[228:229], v[228:229], 0, v[232:233]
	global_load_dword v172, v[224:225], off
	global_load_dwordx2 v[194:195], v[228:229], off
	v_lshl_add_u64 v[224:225], v[224:225], 0, v[230:231]
	v_lshl_add_u64 v[228:229], v[228:229], 0, v[232:233]
	global_load_dword v173, v[224:225], off
	global_load_dwordx2 v[196:197], v[228:229], off
	v_lshl_add_u64 v[224:225], v[224:225], 0, v[230:231]
	v_lshl_add_u64 v[228:229], v[228:229], 0, v[232:233]
	global_load_dword v174, v[224:225], off
	global_load_dwordx2 v[198:199], v[228:229], off
	v_lshl_add_u64 v[224:225], v[224:225], 0, v[230:231]
	v_lshl_add_u64 v[228:229], v[228:229], 0, v[232:233]
	global_load_dword v175, v[224:225], off
	global_load_dwordx2 v[200:201], v[228:229], off
	v_lshl_add_u64 v[224:225], v[224:225], 0, v[230:231]
	v_lshl_add_u64 v[228:229], v[228:229], 0, v[232:233]
	global_load_dword v176, v[224:225], off
	global_load_dwordx2 v[202:203], v[228:229], off
	v_lshl_add_u64 v[224:225], v[224:225], 0, v[230:231]
	v_lshl_add_u64 v[228:229], v[228:229], 0, v[232:233]
	global_load_dword v177, v[224:225], off
	global_load_dwordx2 v[204:205], v[228:229], off
	v_lshl_add_u64 v[224:225], v[224:225], 0, v[230:231]
	v_lshl_add_u64 v[228:229], v[228:229], 0, v[232:233]
	global_load_dword v180, v[224:225], off
	global_load_dwordx2 v[206:207], v[228:229], off
	v_lshl_add_u64 v[224:225], v[224:225], 0, v[230:231]
	v_lshl_add_u64 v[228:229], v[228:229], 0, v[232:233]
	global_load_dword v181, v[224:225], off
	global_load_dwordx2 v[208:209], v[228:229], off
	v_lshl_add_u64 v[224:225], v[224:225], 0, v[230:231]
	v_lshl_add_u64 v[228:229], v[228:229], 0, v[232:233]
	global_load_dword v182, v[224:225], off
	global_load_dwordx2 v[210:211], v[228:229], off
	v_lshl_add_u64 v[224:225], v[224:225], 0, v[230:231]
	v_lshl_add_u64 v[228:229], v[228:229], 0, v[232:233]
	global_load_dword v183, v[224:225], off
	global_load_dwordx2 v[212:213], v[228:229], off
	v_lshl_add_u64 v[224:225], v[224:225], 0, v[230:231]
	v_lshl_add_u64 v[228:229], v[228:229], 0, v[232:233]
	global_load_dword v184, v[224:225], off
	global_load_dwordx2 v[214:215], v[228:229], off
	v_lshl_add_u64 v[224:225], v[224:225], 0, v[230:231]
	v_lshl_add_u64 v[228:229], v[228:229], 0, v[232:233]
	global_load_dword v185, v[224:225], off
	global_load_dwordx2 v[216:217], v[228:229], off
	v_lshl_add_u64 v[224:225], v[224:225], 0, v[230:231]
	v_lshl_add_u64 v[228:229], v[228:229], 0, v[232:233]
	v_lshlrev_b32_e32 v21, 5, v0
	v_cvt_f32_u32_e32 v21, v21
	v_lshlrev_b32_e32 v2, 7, v0
	v_mul_f32_e32 v3, 0x38800000, v3
	v_cos_f32_e32 v22, v3
	v_sin_f32_e32 v30, v3
	v_mul_f32_e32 v3, 0x38800000, v21
	v_cos_f32_e32 v32, v3
	v_sin_f32_e32 v34, v3
	v_lshlrev_b32_e32 v3, 4, v0
	v_cvt_f32_u32_e32 v3, v3
	v_cvt_f32_u32_e32 v2, v2
	v_mul_f32_e32 v40, 0xbf3504f3, v32
	v_mul_f32_e32 v42, 0xbf3504f3, v34
	v_mul_f32_e32 v3, 0x38800000, v3
	v_cos_f32_e32 v52, v3
	v_sin_f32_e32 v54, v3
	v_mul_f32_e32 v20, 0x38800000, v2
	v_cos_f32_e32 v2, v20
	v_sin_f32_e32 v20, v20
	v_mul_f32_e32 v56, 0xbf6c835e, v52
	v_mul_f32_e32 v58, 0xbec3ef15, v54
	v_mul_f32_e32 v62, 0x3ec3ef15, v52
	v_mul_f32_e32 v66, 0xbf3504f3, v52
	v_mul_f32_e32 v68, 0xbf3504f3, v54
	v_mul_f32_e32 v74, 0xbf6c835e, v54
	v_fma_f32 v36, v22, 0, -v30
	v_fma_f32 v38, v30, s39, -v22
	v_fmamk_f32 v44, v32, 0x3f3504f3, v42
	v_fmamk_f32 v46, v34, 0xbf3504f3, v40
	v_fma_f32 v48, v32, 0, -v34
	v_fma_f32 v50, v34, s39, -v32
	v_fmac_f32_e32 v42, 0xbf3504f3, v32
	v_fmac_f32_e32 v40, 0x3f3504f3, v34
	v_fmamk_f32 v60, v52, 0x3f6c835e, v58
	v_fma_f32 v64, v54, s80, -v62
	v_fmamk_f32 v70, v52, 0x3f3504f3, v68
	v_fmamk_f32 v72, v54, 0xbf3504f3, v66
	v_fmamk_f32 v76, v54, 0xbec3ef15, v56
	v_fma_f32 v78, v52, 0, -v54
	v_fma_f32 v80, v54, s39, -v52
	v_fmac_f32_e32 v74, 0xbec3ef15, v52
	v_fmac_f32_e32 v56, 0x3ec3ef15, v54
	v_fmac_f32_e32 v68, 0xbf3504f3, v52
	v_fmac_f32_e32 v66, 0x3f3504f3, v54
	v_fmac_f32_e32 v58, 0xbf6c835e, v52
	v_fma_f32 v82, v54, s14, -v62
	v_fmac_f32_e32 v62, 0xbf6c835e, v54
	v_mov_b32_e32 v59, v58
	v_mov_b32_e32 v69, v68
	v_mov_b32_e32 v75, v74
	v_mov_b32_e32 v79, v78
	v_mov_b32_e32 v63, v62
	v_mov_b32_e32 v71, v70
	v_mov_b32_e32 v61, v60
	v_mov_b32_e32 v53, v52
	v_mov_b32_e32 v43, v42
	v_mov_b32_e32 v41, v40
	v_mov_b32_e32 v49, v48
	v_mov_b32_e32 v51, v50
	v_mov_b32_e32 v45, v44
	v_mov_b32_e32 v47, v46
	v_mov_b32_e32 v33, v32
	v_mov_b32_e32 v35, v34
	v_mov_b32_e32 v37, v36
	v_mov_b32_e32 v39, v38
	v_mov_b32_e32 v23, v22
	v_mov_b32_e32 v31, v30
	v_mov_b32_e32 v3, v2
	v_mov_b32_e32 v21, v20
	v_mov_b32_e32 v55, v54
	v_mov_b32_e32 v65, v64
	v_mov_b32_e32 v73, v72
	v_mov_b32_e32 v77, v76
	v_mov_b32_e32 v81, v80
	v_mov_b32_e32 v57, v56
	v_mov_b32_e32 v67, v66
	v_mov_b32_e32 v83, v82
	v_add_u32_e32 v25, 0xfffffe00, v111
	v_lshlrev_b32_e32 v111, 4, v111
	s_mov_b64 s[12:13], 0

.LBB0_703:
	s_or_b64 exec, exec, s[2:3]
	s_waitcnt vmcnt(0)
	v_lshlrev_b32_e32 v220, 16, v168
	v_and_b32_e32 v221, 0xffff0000, v168
	v_bfe_u32 v222, v218, 16, 1
	v_bfe_u32 v223, v219, 16, 1
	v_add3_u32 v222, v218, v222, v234
	v_add3_u32 v223, v219, v223, v234
	v_lshrrev_b32_e32 v222, 16, v222
	v_and_or_b32 v222, v223, v235, v222
	global_store_dword v[226:227], v222, off
	v_pk_fma_f32 v[218:219], v[186:187], v[218:219], v[220:221]
	v_lshl_add_u64 v[226:227], v[226:227], 0, v[230:231]
	v_lshlrev_b32_e32 v220, 16, v169
	v_and_b32_e32 v221, 0xffff0000, v169
	v_bfe_u32 v222, v218, 16, 1
	v_bfe_u32 v223, v219, 16, 1
	v_add3_u32 v222, v218, v222, v234
	v_add3_u32 v223, v219, v223, v234
	v_lshrrev_b32_e32 v222, 16, v222
	v_and_or_b32 v222, v223, v235, v222
	global_store_dword v[226:227], v222, off
	v_pk_fma_f32 v[218:219], v[188:189], v[218:219], v[220:221]
	v_lshl_add_u64 v[226:227], v[226:227], 0, v[230:231]
	v_lshlrev_b32_e32 v220, 16, v170
	v_and_b32_e32 v221, 0xffff0000, v170
	v_bfe_u32 v222, v218, 16, 1
	v_bfe_u32 v223, v219, 16, 1
	v_add3_u32 v222, v218, v222, v234
	v_add3_u32 v223, v219, v223, v234
	v_lshrrev_b32_e32 v222, 16, v222
	v_and_or_b32 v222, v223, v235, v222
	global_store_dword v[226:227], v222, off
	v_pk_fma_f32 v[218:219], v[190:191], v[218:219], v[220:221]
	v_lshl_add_u64 v[226:227], v[226:227], 0, v[230:231]
	v_lshlrev_b32_e32 v220, 16, v171
	v_and_b32_e32 v221, 0xffff0000, v171
	v_bfe_u32 v222, v218, 16, 1
	v_bfe_u32 v223, v219, 16, 1
	v_add3_u32 v222, v218, v222, v234
	v_add3_u32 v223, v219, v223, v234
	v_lshrrev_b32_e32 v222, 16, v222
	v_and_or_b32 v222, v223, v235, v222
	global_store_dword v[226:227], v222, off
	v_pk_fma_f32 v[218:219], v[192:193], v[218:219], v[220:221]
	v_lshl_add_u64 v[226:227], v[226:227], 0, v[230:231]
	v_lshlrev_b32_e32 v220, 16, v172
	v_and_b32_e32 v221, 0xffff0000, v172
	v_bfe_u32 v222, v218, 16, 1
	v_bfe_u32 v223, v219, 16, 1
	v_add3_u32 v222, v218, v222, v234
	v_add3_u32 v223, v219, v223, v234
	v_lshrrev_b32_e32 v222, 16, v222
	v_and_or_b32 v222, v223, v235, v222
	global_store_dword v[226:227], v222, off
	v_pk_fma_f32 v[218:219], v[194:195], v[218:219], v[220:221]
	v_lshl_add_u64 v[226:227], v[226:227], 0, v[230:231]
	v_lshlrev_b32_e32 v220, 16, v173
	v_and_b32_e32 v221, 0xffff0000, v173
	v_bfe_u32 v222, v218, 16, 1
	v_bfe_u32 v223, v219, 16, 1
	v_add3_u32 v222, v218, v222, v234
	v_add3_u32 v223, v219, v223, v234
	v_lshrrev_b32_e32 v222, 16, v222
	v_and_or_b32 v222, v223, v235, v222
	global_store_dword v[226:227], v222, off
	v_pk_fma_f32 v[218:219], v[196:197], v[218:219], v[220:221]
	v_lshl_add_u64 v[226:227], v[226:227], 0, v[230:231]
	v_lshlrev_b32_e32 v220, 16, v174
	v_and_b32_e32 v221, 0xffff0000, v174
	v_bfe_u32 v222, v218, 16, 1
	v_bfe_u32 v223, v219, 16, 1
	v_add3_u32 v222, v218, v222, v234
	v_add3_u32 v223, v219, v223, v234
	v_lshrrev_b32_e32 v222, 16, v222
	v_and_or_b32 v222, v223, v235, v222
	global_store_dword v[226:227], v222, off
	v_pk_fma_f32 v[218:219], v[198:199], v[218:219], v[220:221]
	v_lshl_add_u64 v[226:227], v[226:227], 0, v[230:231]
	v_lshlrev_b32_e32 v220, 16, v175
	v_and_b32_e32 v221, 0xffff0000, v175
	v_bfe_u32 v222, v218, 16, 1
	v_bfe_u32 v223, v219, 16, 1
	v_add3_u32 v222, v218, v222, v234
	v_add3_u32 v223, v219, v223, v234
	v_lshrrev_b32_e32 v222, 16, v222
	v_and_or_b32 v222, v223, v235, v222
	global_store_dword v[226:227], v222, off
	v_pk_fma_f32 v[218:219], v[200:201], v[218:219], v[220:221]
	v_lshl_add_u64 v[226:227], v[226:227], 0, v[230:231]
	v_lshlrev_b32_e32 v220, 16, v176
	v_and_b32_e32 v221, 0xffff0000, v176
	v_bfe_u32 v222, v218, 16, 1
	v_bfe_u32 v223, v219, 16, 1
	v_add3_u32 v222, v218, v222, v234
	v_add3_u32 v223, v219, v223, v234
	v_lshrrev_b32_e32 v222, 16, v222
	v_and_or_b32 v222, v223, v235, v222
	global_store_dword v[226:227], v222, off
	v_pk_fma_f32 v[218:219], v[202:203], v[218:219], v[220:221]
	v_lshl_add_u64 v[226:227], v[226:227], 0, v[230:231]
	v_lshlrev_b32_e32 v220, 16, v177
	v_and_b32_e32 v221, 0xffff0000, v177
	v_bfe_u32 v222, v218, 16, 1
	v_bfe_u32 v223, v219, 16, 1
	v_add3_u32 v222, v218, v222, v234
	v_add3_u32 v223, v219, v223, v234
	v_lshrrev_b32_e32 v222, 16, v222
	v_and_or_b32 v222, v223, v235, v222
	global_store_dword v[226:227], v222, off
	v_pk_fma_f32 v[218:219], v[204:205], v[218:219], v[220:221]
	v_lshl_add_u64 v[226:227], v[226:227], 0, v[230:231]
	v_lshlrev_b32_e32 v220, 16, v180
	v_and_b32_e32 v221, 0xffff0000, v180
	v_bfe_u32 v222, v218, 16, 1
	v_bfe_u32 v223, v219, 16, 1
	v_add3_u32 v222, v218, v222, v234
	v_add3_u32 v223, v219, v223, v234
	v_lshrrev_b32_e32 v222, 16, v222
	v_and_or_b32 v222, v223, v235, v222
	global_store_dword v[226:227], v222, off
	v_pk_fma_f32 v[218:219], v[206:207], v[218:219], v[220:221]
	v_lshl_add_u64 v[226:227], v[226:227], 0, v[230:231]
	v_lshlrev_b32_e32 v220, 16, v181
	v_and_b32_e32 v221, 0xffff0000, v181
	v_bfe_u32 v222, v218, 16, 1
	v_bfe_u32 v223, v219, 16, 1
	v_add3_u32 v222, v218, v222, v234
	v_add3_u32 v223, v219, v223, v234
	v_lshrrev_b32_e32 v222, 16, v222
	v_and_or_b32 v222, v223, v235, v222
	global_store_dword v[226:227], v222, off
	v_pk_fma_f32 v[218:219], v[208:209], v[218:219], v[220:221]
	v_lshl_add_u64 v[226:227], v[226:227], 0, v[230:231]
	v_lshlrev_b32_e32 v220, 16, v182
	v_and_b32_e32 v221, 0xffff0000, v182
	v_bfe_u32 v222, v218, 16, 1
	v_bfe_u32 v223, v219, 16, 1
	v_add3_u32 v222, v218, v222, v234
	v_add3_u32 v223, v219, v223, v234
	v_lshrrev_b32_e32 v222, 16, v222
	v_and_or_b32 v222, v223, v235, v222
	global_store_dword v[226:227], v222, off
	v_pk_fma_f32 v[218:219], v[210:211], v[218:219], v[220:221]
	v_lshl_add_u64 v[226:227], v[226:227], 0, v[230:231]
	v_lshlrev_b32_e32 v220, 16, v183
	v_and_b32_e32 v221, 0xffff0000, v183
	v_bfe_u32 v222, v218, 16, 1
	v_bfe_u32 v223, v219, 16, 1
	v_add3_u32 v222, v218, v222, v234
	v_add3_u32 v223, v219, v223, v234
	v_lshrrev_b32_e32 v222, 16, v222
	v_and_or_b32 v222, v223, v235, v222
	global_store_dword v[226:227], v222, off
	v_pk_fma_f32 v[218:219], v[212:213], v[218:219], v[220:221]
	v_lshl_add_u64 v[226:227], v[226:227], 0, v[230:231]
	v_lshlrev_b32_e32 v220, 16, v184
	v_and_b32_e32 v221, 0xffff0000, v184
	v_bfe_u32 v222, v218, 16, 1
	v_bfe_u32 v223, v219, 16, 1
	v_add3_u32 v222, v218, v222, v234
	v_add3_u32 v223, v219, v223, v234
	v_lshrrev_b32_e32 v222, 16, v222
	v_and_or_b32 v222, v223, v235, v222
	global_store_dword v[226:227], v222, off
	v_pk_fma_f32 v[218:219], v[214:215], v[218:219], v[220:221]
	v_lshl_add_u64 v[226:227], v[226:227], 0, v[230:231]
	v_lshlrev_b32_e32 v220, 16, v185
	v_and_b32_e32 v221, 0xffff0000, v185
	v_bfe_u32 v222, v218, 16, 1
	v_bfe_u32 v223, v219, 16, 1
	v_add3_u32 v222, v218, v222, v234
	v_add3_u32 v223, v219, v223, v234
	v_lshrrev_b32_e32 v222, 16, v222
	v_and_or_b32 v222, v223, v235, v222
	global_store_dword v[226:227], v222, off
	v_pk_fma_f32 v[218:219], v[216:217], v[218:219], v[220:221]
	v_lshl_add_u64 v[226:227], v[226:227], 0, v[230:231]
	s_nop 0
	v_add_f32_e32 v0, 0, v8
	v_add_f32_e32 v0, v0, v9
	v_add_f32_e32 v0, v0, v10
	v_add_f32_e32 v0, v0, v11
	v_add_f32_e32 v0, v0, v4
	v_add_f32_e32 v0, v0, v5
	v_add_f32_e32 v0, v0, v6
	v_add_f32_e32 v0, v0, v7
	v_div_scale_f32 v3, s[2:3], v0, v0, 1.0
	v_rcp_f32_e32 v4, v3
	v_add_f32_e32 v2, 0, v16
	v_add_f32_e32 v2, v2, v17
	v_add_f32_e32 v2, v2, v18
	v_fma_f32 v5, -v3, v4, 1.0
	v_fmac_f32_e32 v4, v5, v4
	v_div_scale_f32 v5, vcc, 1.0, v0, 1.0
	v_add_f32_e32 v2, v2, v19
	v_mul_f32_e32 v6, v5, v4
	v_add_f32_e32 v2, v2, v12
	v_fma_f32 v7, -v3, v6, v5
	v_add_f32_e32 v2, v2, v13
	v_fmac_f32_e32 v6, v7, v4
	v_add_f32_e32 v2, v2, v14
	v_fma_f32 v3, -v3, v6, v5
	v_add_f32_e32 v2, v2, v15
	v_div_fmas_f32 v3, v3, v4, v6
	v_div_fixup_f32 v0, v3, v0, 1.0
	v_div_scale_f32 v3, s[2:3], v2, v2, 1.0
	v_rcp_f32_e32 v4, v3
	v_readlane_b32 s52, v253, 23
	s_lshl_b64 s[2:3], s[28:29], 2
	v_readlane_b32 s58, v253, 29
	v_fma_f32 v5, -v3, v4, 1.0
	v_fmac_f32_e32 v4, v5, v4
	v_div_scale_f32 v5, vcc, 1.0, v2, 1.0
	v_mul_f32_e32 v6, v5, v4
	v_fma_f32 v7, -v3, v6, v5
	v_fmac_f32_e32 v6, v7, v4
	v_fma_f32 v3, -v3, v6, v5
	v_readlane_b32 s59, v253, 30
	s_add_u32 s2, s58, s2
	v_div_fmas_f32 v3, v3, v4, v6
	s_addc_u32 s3, s59, s3
	v_div_fixup_f32 v25, v3, v2, 1.0
	s_waitcnt lgkmcnt(0)
	s_barrier
	global_load_dwordx2 v[2:3], v1, s[2:3]
	s_lshl_b64 s[2:3], s[28:29], 13
	s_lshl_b64 s[10:11], s[10:11], 13
	s_mov_b32 s20, 0
	s_mov_b64 s[12:13], -1
	v_readlane_b32 s53, v253, 24
	v_readlane_b32 s54, v253, 25
	v_readlane_b32 s55, v253, 26
	v_readlane_b32 s56, v253, 27
	v_readlane_b32 s57, v253, 28
	v_readlane_b32 s60, v253, 31
	v_readlane_b32 s61, v253, 32
	v_readlane_b32 s62, v253, 33
	v_readlane_b32 s63, v253, 34
	v_readlane_b32 s64, v253, 35
	v_readlane_b32 s65, v253, 36
	v_readlane_b32 s66, v253, 37
	v_readlane_b32 s67, v253, 38

.LBB0_706:
	s_waitcnt vmcnt(0)
	v_readlane_b32 s82, v253, 55
	v_readlane_b32 s83, v253, 56
	s_barrier
	v_readfirstlane_b32 vcc_lo, v252
	s_lshr_b32 vcc_lo, vcc_lo, 6
	s_cmp_lg_u32 vcc_lo, 1
	s_cbranch_scc1 .Lbar_noinv_5
	buffer_inv sc1
.Lbar_noinv_5:
	s_and_saveexec_b64 s[0:1], s[82:83]
	v_readlane_b32 s80, v253, 3
	v_readlane_b32 s81, v253, 4
	v_readlane_b32 s86, v254, 56
	v_readlane_b32 s88, v253, 1
	v_readlane_b32 s92, v254, 46
	v_readlane_b32 s94, v254, 34
	v_readlane_b32 s10, v255, 6
	s_mov_b32 s78, s46
	v_readlane_b32 s87, v254, 57
	v_readlane_b32 s89, v253, 2
	v_readlane_b32 s93, v254, 47
	v_readlane_b32 s95, v254, 35
	v_readlane_b32 s79, v254, 19
	v_readlane_b32 s11, v255, 7
	v_readlane_b32 s81, v254, 44
	s_cbranch_execz .LBB0_758
	s_add_i32 s2, 0, 0x23fc0
	v_mov_b32_e32 v0, s2
	s_add_i32 s2, 0, 0x23fc4
	s_waitcnt vmcnt(0) expcnt(0) lgkmcnt(0)
	ds_read_b32 v2, v0
	v_mov_b32_e32 v0, s2
	s_add_i32 s2, 0, 0x23fc8
	v_mov_b32_e32 v1, s2
	ds_read_b32 v0, v0
	ds_read_b32 v1, v1
	s_waitcnt lgkmcnt(2)
	v_cmp_ne_u32_e32 vcc, 0, v2
	s_waitcnt lgkmcnt(0)
	v_readfirstlane_b32 s8, v1
	s_cbranch_vccnz .LBB0_722
	s_mov_b32 s9, 1
	v_mov_b32_e32 v16, 0
	s_branch .LBB0_710

.LBB0_758:
	s_or_b64 exec, exec, s[0:1]
	v_readlane_b32 s0, v254, 13
	v_mov_b32_e32 v3, v252
	v_readlane_b32 s1, v254, 14
	s_mov_b64 s[76:77], s[50:51]
	s_waitcnt vmcnt(0) lgkmcnt(0)
	s_barrier
	s_and_b64 vcc, exec, s[0:1]
	v_readfirstlane_b32 s3, v3
	s_cbranch_vccz .LBB0_781
	v_lshlrev_b32_e32 v4, 2, v3
	v_readlane_b32 s4, v255, 0
	v_ashrrev_i32_e32 v5, 31, v4
	v_readlane_b32 s5, v255, 1
	s_movk_i32 s15, 0x1800
	v_readlane_b32 s44, v253, 39
	v_lshl_add_u64 v[56:57], v[4:5], 2, s[4:5]
	v_ashrrev_i32_e32 v5, 3, v3
	v_and_b32_e32 v147, 0xffffffe0, v5
	v_or_b32_e32 v16, 8, v147
	v_mad_i64_i32 v[76:77], s[4:5], v16, s15, 0
	v_or_b32_e32 v16, 9, v147
	v_mad_i64_i32 v[78:79], s[4:5], v16, s15, 0
	v_or_b32_e32 v16, 10, v147
	v_mad_i64_i32 v[80:81], s[4:5], v16, s15, 0
	v_or_b32_e32 v16, 11, v147
	v_mad_i64_i32 v[82:83], s[4:5], v16, s15, 0
	v_or_b32_e32 v16, 12, v147
	v_mad_i64_i32 v[84:85], s[4:5], v16, s15, 0
	v_or_b32_e32 v16, 13, v147
	v_mad_i64_i32 v[86:87], s[4:5], v16, s15, 0
	v_or_b32_e32 v16, 14, v147
	v_mad_i64_i32 v[88:89], s[4:5], v16, s15, 0
	v_or_b32_e32 v16, 15, v147
	v_mad_i64_i32 v[90:91], s[4:5], v16, s15, 0
	v_or_b32_e32 v16, 16, v147
	v_mad_i64_i32 v[92:93], s[4:5], v16, s15, 0
	v_or_b32_e32 v16, 17, v147
	v_mad_i64_i32 v[94:95], s[4:5], v16, s15, 0
	v_or_b32_e32 v16, 18, v147
	v_and_b32_e32 v6, -8, v5
	v_mad_i64_i32 v[96:97], s[4:5], v16, s15, 0
	v_or_b32_e32 v16, 19, v147
	v_mad_i64_i32 v[98:99], s[4:5], v16, s15, 0
	v_or_b32_e32 v16, 20, v147
	v_or_b32_e32 v17, 25, v6
	v_readlane_b32 s48, v253, 43
	v_readlane_b32 s49, v253, 44
	v_readlane_b32 s50, v253, 45
	v_readlane_b32 s51, v253, 46
	v_readlane_b32 s52, v253, 47
	v_readlane_b32 s53, v253, 48
	v_readlane_b32 s54, v253, 49
	v_readlane_b32 s55, v253, 50
	v_readlane_b32 s56, v253, 51
	v_readlane_b32 s57, v253, 52
	v_readlane_b32 s58, v253, 53
	v_readlane_b32 s59, v253, 54
	v_mad_i64_i32 v[100:101], s[4:5], v16, s15, 0
	v_or_b32_e32 v16, 21, v147
	v_mad_i64_i32 v[110:111], s[4:5], v17, s15, 0
	v_or_b32_e32 v17, 26, v6
	s_add_i32 s8, 0, 0x11000
	v_mad_i64_i32 v[102:103], s[4:5], v16, s15, 0
	v_or_b32_e32 v16, 22, v147
	v_mad_i64_i32 v[112:113], s[4:5], v17, s15, 0
	v_or_b32_e32 v17, 27, v6
	v_readlane_b32 s48, v253, 23
	v_and_b32_e32 v2, 0xff, v3
	s_movk_i32 s9, 0x90
	v_mov_b32_e32 v4, s8
	v_mad_i64_i32 v[104:105], s[4:5], v16, s15, 0
	v_or_b32_e32 v16, 23, v147
	v_mad_i64_i32 v[114:115], s[4:5], v17, s15, 0
	v_or_b32_e32 v17, 28, v6
	v_readlane_b32 s56, v253, 31
	v_readlane_b32 s57, v253, 32
	v_mad_u32_u24 v4, v2, s9, v4
	v_or_b32_e32 v9, 1, v147
	v_or_b32_e32 v10, 2, v147
	v_or_b32_e32 v11, 3, v147
	v_or_b32_e32 v12, 4, v147
	v_or_b32_e32 v13, 5, v147
	v_or_b32_e32 v14, 6, v147
	v_or_b32_e32 v15, 7, v147
	v_mad_i64_i32 v[106:107], s[4:5], v16, s15, 0
	v_or_b32_e32 v16, 24, v6
	v_mad_i64_i32 v[116:117], s[4:5], v17, s15, 0
	v_or_b32_e32 v17, 29, v6
	v_or_b32_e32 v6, 30, v6
	v_or_b32_e32 v5, 31, v5
	v_readlane_b32 s58, v253, 33
	v_readlane_b32 s59, v253, 34
	v_readlane_b32 s60, v253, 35
	v_readlane_b32 s61, v253, 36
	v_readlane_b32 s62, v253, 37
	v_readlane_b32 s63, v253, 38
	s_mov_b64 s[20:21], s[56:57]
	v_mad_i64_i32 v[60:61], s[4:5], v147, s15, 0
	v_mad_i64_i32 v[62:63], s[4:5], v9, s15, 0
	v_mad_i64_i32 v[64:65], s[4:5], v10, s15, 0
	v_mad_i64_i32 v[66:67], s[4:5], v11, s15, 0
	v_mad_i64_i32 v[68:69], s[4:5], v12, s15, 0
	v_mad_i64_i32 v[70:71], s[4:5], v13, s15, 0
	v_mad_i64_i32 v[72:73], s[4:5], v14, s15, 0
	v_mad_i64_i32 v[74:75], s[4:5], v15, s15, 0
	v_lshl_add_u32 v160, v147, 1, v4
	v_mad_i64_i32 v[108:109], s[4:5], v16, s15, 0
	v_mad_i64_i32 v[118:119], s[4:5], v17, s15, 0
	v_mad_i64_i32 v[120:121], s[4:5], v6, s15, 0
	v_mad_i64_i32 v[122:123], s[4:5], v5, s15, 0
	v_lshl_add_u32 v161, v16, 1, v4
	v_bfe_u32 v4, v3, 7, 1
	s_mov_b64 s[22:23], s[58:59]
	s_mov_b64 s[26:27], s[62:63]
	v_mov_b32_e32 v5, s27
	v_mov_b32_e32 v6, s23
	v_cmp_eq_u32_e64 s[4:5], 0, v4
	v_readlane_b32 s45, v253, 40
	s_mov_b64 s[24:25], s[60:61]
	v_cndmask_b32_e64 v127, v5, v6, s[4:5]
	v_mov_b32_e32 v5, s26
	v_mov_b32_e32 v6, s22
	v_cndmask_b32_e64 v126, v5, v6, s[4:5]
	v_mov_b32_e32 v5, s45
	v_mov_b32_e32 v6, s25
	v_cndmask_b32_e64 v129, v5, v6, s[4:5]
	v_mov_b32_e32 v5, s44
	v_mov_b32_e32 v6, s24
	v_cndmask_b32_e64 v128, v5, v6, s[4:5]
	v_sub_u32_e32 v5, 63, v147
	v_cndmask_b32_e64 v5, v5, v147, s[4:5]
	v_mad_i64_i32 v[130:131], s[12:13], v5, s15, 0
	v_sub_u32_e32 v5, 63, v9
	v_cndmask_b32_e64 v5, v5, v9, s[4:5]
	v_mad_i64_i32 v[132:133], s[12:13], v5, s15, 0
	v_sub_u32_e32 v5, 63, v10
	v_cndmask_b32_e64 v5, v5, v10, s[4:5]
	v_mad_i64_i32 v[134:135], s[12:13], v5, s15, 0
	v_sub_u32_e32 v5, 63, v11
	v_cndmask_b32_e64 v5, v5, v11, s[4:5]
	v_mad_i64_i32 v[136:137], s[12:13], v5, s15, 0
	v_sub_u32_e32 v5, 63, v12
	v_cndmask_b32_e64 v5, v5, v12, s[4:5]
	v_mad_i64_i32 v[138:139], s[12:13], v5, s15, 0
	v_sub_u32_e32 v5, 63, v13
	v_cndmask_b32_e64 v5, v5, v13, s[4:5]
	s_add_i32 s10, 0, 0x1c400
	s_movk_i32 s6, 0xff
	v_mad_i64_i32 v[140:141], s[12:13], v5, s15, 0
	v_sub_u32_e32 v5, 63, v14
	v_bfe_u32 v6, v3, 4, 2
	s_ashr_i32 s26, s3, 7
	v_and_b32_e32 v7, 63, v3
	s_ashr_i32 s2, s3, 6
	v_lshl_add_u32 v125, v3, 4, s10
	v_and_b32_e32 v124, 0x7f, v3
	v_cndmask_b32_e64 v5, v5, v14, s[4:5]
	v_cmp_lt_u32_e64 s[6:7], s6, v3
	v_lshlrev_b32_e32 v163, 6, v4
	v_and_b32_e32 v165, 15, v3
	s_lshl_b32 s3, s26, 4
	v_lshlrev_b32_e32 v9, 2, v6
	v_and_b32_e32 v3, 48, v3
	v_mad_i64_i32 v[142:143], s[12:13], v5, s15, 0
	v_sub_u32_e32 v5, 63, v15
	v_lshlrev_b32_e32 v162, 7, v4
	v_add_u32_e32 v164, s10, v163
	s_lshl_b32 s10, s2, 1
	v_or_b32_e32 v166, s3, v9
	v_or_b32_e32 v4, s3, v165
	v_add_u32_e32 v146, 0, v3
	s_movk_i32 s28, 0x110
	s_lshl_b32 s3, s2, 5
	v_cndmask_b32_e64 v5, v5, v15, s[4:5]
	s_and_b32 s27, s10, 2
	v_mad_u64_u32 v[148:149], s[10:11], v4, s28, v[146:147]
	v_or_b32_e32 v4, s3, v165
	v_mad_i64_i32 v[144:145], s[12:13], v5, s15, 0
	v_mul_lo_u32 v5, v4, s9
	v_add3_u32 v170, s8, v5, v3
	v_ashrrev_i32_e32 v5, 31, v4
	v_lshlrev_b64 v[150:151], 8, v[4:5]
	v_or_b32_e32 v4, 16, v4
	v_ashrrev_i32_e32 v5, 31, v4
	v_lshlrev_b64 v[152:153], 8, v[4:5]
	v_and_b32_e32 v5, 64, v179
	v_xor_b32_e32 v4, 16, v179
	v_add_u32_e32 v5, 64, v5
	v_cmp_lt_i32_e32 vcc, v4, v5
	v_readlane_b32 s46, v253, 41
	v_readlane_b32 s47, v253, 42
	v_cndmask_b32_e32 v4, v179, v4, vcc
	v_lshlrev_b32_e32 v176, 2, v4
	v_xor_b32_e32 v4, 32, v179
	v_cmp_lt_i32_e32 vcc, v4, v5
	s_add_i32 s0, 0, 0x1ec00
	s_add_i32 s29, 0, 0x1a000
	v_cndmask_b32_e32 v4, v179, v4, vcc
	v_or_b32_e32 v173, 48, v7
	v_lshlrev_b32_e32 v177, 2, v4
	v_or_b32_e32 v4, s3, v9
	v_mov_b32_e32 v0, s46
	v_mov_b32_e32 v1, s47
	v_lshl_add_u32 v8, v7, 2, s0
	v_add_u32_e32 v3, s29, v3
	v_mul_u32_u24_e32 v10, 0x90, v165
	v_or_b32_e32 v171, 16, v165
	v_or_b32_e32 v172, 32, v165
	v_mul_u32_u24_e32 v11, 0x90, v173
	v_lshlrev_b32_e32 v6, 3, v6
	s_lshl_b32 s10, s2, 8
	v_ashrrev_i32_e32 v5, 31, v4
	s_mov_b32 s1, 0
	v_mov_b32_e32 v59, 0
	v_mul_lo_u32 v149, v166, s9
	v_or_b32_e32 v167, 1, v166
	v_or_b32_e32 v168, 2, v166
	v_or_b32_e32 v169, 3, v166
	v_mul_u32_u24_e32 v174, 0x110, v165
	v_mul_u32_u24_e32 v175, 0x110, v173
	v_cmp_gt_u32_e64 s[8:9], 16, v7
	v_lshl_add_u32 v178, v165, 2, s0
	v_lshl_add_u32 v180, v171, 2, s0
	v_lshl_add_u32 v181, v172, 2, s0
	v_lshl_add_u32 v182, v173, 2, s0
	v_lshl_add_u64 v[154:155], v[4:5], 2, v[0:1]
	v_sub_u32_e32 v183, 56, v147
	v_lshlrev_b32_e32 v156, 1, v2
	s_mov_b32 s30, 0x5040100
	s_movk_i32 s31, 0x1000
	s_mov_b32 s33, 0xbfb8aa3b
	s_mov_b32 s35, 0x800000
	s_mov_b32 s36, 0x3f317217
	s_mov_b32 s37, 0x7f800000
	s_movk_i32 s38, 0x7fff
	s_movk_i32 s39, 0x88
	v_add_u32_e32 v184, v3, v10
	v_add_u32_e32 v185, v3, v11
	v_lshlrev_b64 v[158:159], 1, v[4:5]
	s_mov_b64 s[2:3], 0x1000
	s_mov_b64 s[12:13], 0x10200800
	s_mov_b32 s14, 0x3b800000
	s_mov_b32 s42, 0x10200000
	v_mov_b32_e32 v186, 0x41b17218
	v_lshlrev_b32_e32 v58, 1, v6
	v_add_u32_e32 v187, s10, v8
	v_mov_b32_e32 v188, 1
	s_mov_b32 s43, s78
	v_readlane_b32 s49, v253, 24
	v_readlane_b32 s50, v253, 25
	v_readlane_b32 s51, v253, 26
	v_readlane_b32 s52, v253, 27
	v_readlane_b32 s53, v253, 28
	v_readlane_b32 s54, v253, 29
	v_readlane_b32 s55, v253, 30
	s_branch .LBB0_761

.Lbar_noinv_6:
	s_and_saveexec_b64 s[0:1], s[82:83]
	v_readlane_b32 s50, v255, 6
	v_readlane_b32 s52, v254, 60
	v_readlane_b32 s51, v255, 7
	s_mov_b64 s[56:57], s[76:77]
	v_readlane_b32 s53, v254, 61
	s_cbranch_execz .LBB0_836
	s_add_i32 s2, 0, 0x23fc0
	v_mov_b32_e32 v0, s2
	s_add_i32 s2, 0, 0x23fc4
	s_waitcnt vmcnt(0) expcnt(0) lgkmcnt(0)
	ds_read_b32 v2, v0
	v_mov_b32_e32 v0, s2
	s_add_i32 s2, 0, 0x23fc8
	v_mov_b32_e32 v1, s2
	ds_read_b32 v0, v0
	ds_read_b32 v1, v1
	s_waitcnt lgkmcnt(2)
	v_cmp_ne_u32_e32 vcc, 0, v2
	s_waitcnt lgkmcnt(0)
	v_readfirstlane_b32 s8, v1
	s_cbranch_vccnz .LBB0_800
	s_mov_b32 s9, 1
	v_mov_b32_e32 v16, 0
	s_branch .LBB0_788

.LBB0_836:
	s_or_b64 exec, exec, s[0:1]
	v_readlane_b32 s0, v255, 4
	v_mov_b32_e32 v9, v252
	v_readlane_b32 s1, v255, 5
	s_waitcnt vmcnt(0) lgkmcnt(0)
	s_barrier
	s_and_b64 vcc, exec, s[0:1]
	v_readfirstlane_b32 s4, v9
	s_cbranch_vccz .LBB0_842
	s_lshr_b32 s0, s81, 29
	s_add_i32 s2, s78, s0
	s_and_b32 s0, s2, -8
	s_sub_i32 s3, s78, s0
	s_cmp_gt_i32 s3, -1
	s_cbranch_scc0 .LBB0_839
	s_lshl_b32 s5, s3, 5
	s_cbranch_execz .LBB0_840
	s_branch .LBB0_841

.Lbar_noinv_7:
	s_and_saveexec_b64 s[2:3], s[82:83]
	s_cbranch_execz .LBB0_944
	s_add_i32 s4, 0, 0x23fc0
	v_mov_b32_e32 v0, s4
	s_add_i32 s4, 0, 0x23fc4
	s_waitcnt vmcnt(0) expcnt(0) lgkmcnt(0)
	ds_read_b32 v2, v0
	v_mov_b32_e32 v0, s4
	s_add_i32 s4, 0, 0x23fc8
	v_mov_b32_e32 v1, s4
	ds_read_b32 v0, v0
	ds_read_b32 v1, v1
	s_waitcnt lgkmcnt(2)
	v_cmp_ne_u32_e32 vcc, 0, v2
	s_waitcnt lgkmcnt(0)
	v_readfirstlane_b32 s10, v1
	s_cbranch_vccnz .LBB0_908
	s_mov_b32 s11, 1
	v_mov_b32_e32 v16, 0
	s_branch .LBB0_896

.LBB0_944:
	s_or_b64 exec, exec, s[2:3]
	v_readlane_b32 s2, v254, 54
	v_mov_b32_e32 v9, v252
	v_readlane_b32 s3, v254, 55
	s_waitcnt vmcnt(0) lgkmcnt(0)
	s_barrier
	s_andn2_b64 vcc, exec, s[2:3]
	v_readfirstlane_b32 s5, v9
	s_cbranch_vccnz .LBB0_960
	v_lshlrev_b32_e32 v0, 4, v9
	v_add_u32_e32 v1, 0x2000, v0
	v_ashrrev_i32_e32 v2, 31, v1
	v_lshrrev_b32_e32 v2, 22, v2
	v_add_u32_e32 v2, v1, v2
	v_ashrrev_i32_e32 v8, 10, v2
	v_mul_i32_i24_e32 v2, 0x400, v8
	v_sub_u32_e32 v1, v1, v2
	v_lshrrev_b32_e32 v2, 4, v1
	v_bitop3_b32 v1, v2, v1, 32 bitop3:0x6c
	v_ashrrev_i32_e32 v2, 31, v1
	v_lshrrev_b32_e32 v2, 26, v2
	v_add_u32_e32 v2, v1, v2
	v_lshlrev_b32_e32 v3, 3, v8
	v_ashrrev_i32_e32 v10, 6, v2
	v_and_b32_e32 v3, -16, v3
	v_add_u32_e32 v3, v10, v3
	v_and_b32_e32 v4, 3, v10
	s_mov_b32 s2, 0xfffe0
	v_lshrrev_b32_e32 v5, 2, v3
	v_lshlrev_b32_e32 v6, 1, v3
	v_and_b32_e32 v2, 0xc0, v2
	v_and_or_b32 v4, v3, s2, v4
	v_and_b32_e32 v5, 4, v5
	v_and_b32_e32 v6, 24, v6
	v_sub_u32_e32 v1, v1, v2
	v_mov_b32_e32 v2, 1
	v_or3_b32 v4, v4, v5, v6
	v_lshlrev_b32_e32 v5, 5, v8
	v_ashrrev_i16_sdwa v1, v2, sext(v1) dst_sel:DWORD dst_unused:UNUSED_PAD src0_sel:DWORD src1_sel:BYTE_0
	v_and_b32_e32 v5, 32, v5
	v_bfe_i32 v11, v1, 0, 16
	v_add_lshl_u32 v1, v5, v11, 1
	v_lshl_add_u32 v128, v4, 12, v1
	v_lshl_add_u32 v130, v3, 12, v1
	v_bfe_i32 v1, v9, 27, 1
	v_lshrrev_b32_e32 v1, 22, v1
	v_add_u32_e32 v1, v0, v1
	v_and_b32_e32 v1, 0xfffffc00, v1
	v_sub_u32_e32 v0, v0, v1
	v_lshrrev_b32_e32 v1, 4, v0
	v_ashrrev_i32_e32 v3, 31, v9
	v_bitop3_b32 v0, v1, v0, 32 bitop3:0x6c
	v_lshrrev_b32_e32 v3, 26, v3
	v_ashrrev_i32_e32 v1, 31, v0
	v_add_u32_e32 v3, v9, v3
	v_lshrrev_b32_e32 v1, 26, v1
	v_ashrrev_i32_e32 v13, 6, v3
	v_add_u32_e32 v1, v0, v1
	v_lshlrev_b32_e32 v3, 3, v13
	v_ashrrev_i32_e32 v12, 6, v1
	v_and_b32_e32 v3, -16, v3
	v_add_u32_e32 v3, v12, v3
	v_and_b32_e32 v4, 3, v12
	v_and_or_b32 v4, v3, s2, v4
	s_lshr_b32 s2, s81, 29
	s_add_i32 s2, s78, s2
	s_ashr_i32 s8, s5, 6
	s_ashr_i32 s3, s2, 3
	s_and_b32 s2, s2, -8
	s_ashr_i32 s10, s5, 8
	s_lshl_b32 s20, s8, 10
	s_sub_i32 s2, s78, s2
	s_cmp_lt_i32 s2, 0
	s_movk_i32 s21, 0xb1
	s_cselect_b32 s4, s21, 0xb0
	s_mul_i32 s2, s2, s4
	s_add_i32 s2, s2, s3
	s_mul_hi_i32 s3, s2, 0x2e8ba2e9
	s_lshr_b32 s4, s3, 31
	s_ashr_i32 s3, s3, 6
	s_add_i32 s3, s3, s4
	s_lshl_b32 s6, s3, 3
	s_mulk_i32 s3, 0x160
	s_sub_i32 s2, s2, s3
	s_sext_i32_i16 s3, s2
	s_bfe_u32 s3, s3, 0x3001c
	s_add_i32 s3, s2, s3
	s_sext_i32_i16 s4, s3
	s_and_b32 s3, s3, 0xfff8
	s_sub_i32 s2, s2, s3
	s_sext_i32_i16 s2, s2
	v_lshrrev_b32_e32 v5, 2, v3
	v_lshlrev_b32_e32 v6, 1, v3
	v_and_b32_e32 v1, 0xc0, v1
	s_lshr_b32 s4, s4, 3
	s_add_i32 s6, s6, s2
	v_and_b32_e32 v5, 4, v5
	v_and_b32_e32 v6, 24, v6
	v_sub_u32_e32 v0, v0, v1
	s_ashr_i32 s7, s6, 31
	s_bfe_i64 s[12:13], s[4:5], 0x100000
	v_or3_b32 v4, v4, v5, v6
	v_lshlrev_b32_e32 v5, 5, v13
	v_ashrrev_i16_sdwa v0, v2, sext(v0) dst_sel:DWORD dst_unused:UNUSED_PAD src0_sel:DWORD src1_sel:BYTE_0
	s_lshl_b64 s[2:3], s[6:7], 20
	s_lshl_b64 s[12:13], s[12:13], 20
	v_and_b32_e32 v5, 32, v5
	v_bfe_i32 v14, v0, 0, 16
	s_add_u32 s30, s40, s12
	v_add_lshl_u32 v0, v5, v14, 1
	s_addc_u32 s31, s41, s13
	s_add_i32 s22, s20, 0
	v_lshl_add_u32 v132, v4, 12, v0
	v_and_b32_e32 v238, 15, v9
	v_lshl_or_b32 v238, s10, 6, v238
	v_lshl_add_u32 v238, s6, 8, v238
	v_lshlrev_b32_e32 v238, 2, v238
	global_load_dword v230, v238, s[0:1]
	global_load_dword v231, v238, s[0:1] offset:64
	global_load_dword v232, v238, s[0:1] offset:128
	global_load_dword v233, v238, s[0:1] offset:192
	global_load_dword v234, v238, s[0:1] offset:512
	global_load_dword v235, v238, s[0:1] offset:576
	global_load_dword v236, v238, s[0:1] offset:640
	global_load_dword v237, v238, s[0:1] offset:704
	s_add_i32 m0, s22, 0x10000
	v_lshl_add_u32 v134, v3, 12, v0
	global_load_lds_dwordx4 v132, s[30:31]
	s_add_i32 m0, s22, 0x12000
	s_add_u32 s12, s30, 0x80000
	global_load_lds_dwordx4 v128, s[30:31]
	s_addc_u32 s13, s31, 0
	s_add_i32 m0, s22, 0x14000
	v_mov_b32_e32 v133, 0
	global_load_lds_dwordx4 v132, s[12:13]
	s_add_i32 m0, s22, 0x16000
	s_add_u32 s28, s18, s2
	s_addc_u32 s29, s19, s3
	s_add_i32 s23, s22, 0x2000
	global_load_lds_dwordx4 v128, s[12:13]
	s_mov_b32 m0, s22
	s_add_u32 s2, s28, 0x80000
	global_load_lds_dwordx4 v134, s[28:29]
	s_mov_b32 m0, s23
	s_addc_u32 s3, s29, 0
	s_add_i32 s33, s22, 0x4000
	global_load_lds_dwordx4 v130, s[28:29]
	s_mov_b32 m0, s33
	s_add_i32 s35, s22, 0x6000
	global_load_lds_dwordx4 v134, s[2:3]
	s_mov_b32 m0, s35
	v_mov_b32_e32 v129, v133
	global_load_lds_dwordx4 v130, s[2:3]
	v_mov_b32_e32 v135, v133
	v_mov_b32_e32 v131, v133
	s_cmp_eq_u32 s10, 1
	s_mov_b32 s36, 0
	v_lshl_add_u64 v[6:7], s[30:31], 0, v[132:133]
	v_lshl_add_u64 v[4:5], s[30:31], 0, v[128:129]
	v_lshl_add_u64 v[0:1], s[28:29], 0, v[134:135]
	s_cselect_b64 s[2:3], -1, 0
	s_cmp_lg_u32 s10, 1
	v_lshl_add_u64 v[2:3], s[28:29], 0, v[130:131]
	s_cbranch_scc1 .LBB0_947
	s_barrier

.Lbar_noinv_8:
	s_and_saveexec_b64 s[0:1], s[82:83]
	s_cbranch_execz .LBB0_1017
	s_add_i32 s2, 0, 0x23fc0
	v_mov_b32_e32 v0, s2
	s_add_i32 s2, 0, 0x23fc4
	s_waitcnt vmcnt(0) expcnt(0) lgkmcnt(0)
	ds_read_b32 v2, v0
	v_mov_b32_e32 v0, s2
	s_add_i32 s2, 0, 0x23fc8
	v_mov_b32_e32 v1, s2
	ds_read_b32 v0, v0
	ds_read_b32 v1, v1
	s_waitcnt lgkmcnt(2)
	v_cmp_ne_u32_e32 vcc, 0, v2
	s_waitcnt lgkmcnt(0)
	v_readfirstlane_b32 s8, v1
	s_cbranch_vccnz .LBB0_981
	s_mov_b32 s9, 1
	v_mov_b32_e32 v16, 0
	s_branch .LBB0_969

.LBB0_1017:
	s_or_b64 exec, exec, s[0:1]
	v_readlane_b32 s0, v254, 58
	v_readlane_b32 s48, v253, 39
	v_readlane_b32 s1, v254, 59
	v_readlane_b32 s54, v253, 45
	v_readlane_b32 s55, v253, 46
	v_readlane_b32 s62, v253, 53
	v_readlane_b32 s63, v253, 54
	s_waitcnt vmcnt(0) lgkmcnt(0)
	s_barrier
	s_and_b64 vcc, exec, s[0:1]
	v_readfirstlane_b32 s4, v252
	s_mov_b64 s[54:55], s[62:63]
	v_readlane_b32 s49, v253, 40
	v_readlane_b32 s50, v253, 41
	v_readlane_b32 s51, v253, 42
	v_readlane_b32 s52, v253, 43
	v_readlane_b32 s53, v253, 44
	v_readlane_b32 s56, v253, 47
	v_readlane_b32 s57, v253, 48
	v_readlane_b32 s58, v253, 49
	v_readlane_b32 s59, v253, 50
	v_readlane_b32 s60, v253, 51
	v_readlane_b32 s61, v253, 52
	s_cbranch_vccnz .LBB0_1023
	s_lshr_b32 s0, s81, 29
	s_add_i32 s5, s78, s0
	s_and_b32 s0, s5, -8
	s_sub_i32 s2, s78, s0
	s_cmp_gt_i32 s2, -1
	s_cbranch_scc0 .LBB0_1020
	s_lshl_b32 s3, s2, 5
	s_ashr_i32 s0, s5, 3
	s_cbranch_execz .LBB0_1021
	s_branch .LBB0_1022
